# RG-LRU gate math re-emitted with packed f32 ops (v_pk_add/mul/fma, same operations and order per channel): 26 fewer VALU issues per 4-channel block
# speedup vs baseline: 1.0148x; 1.0048x over previous
; #define LAS __attribute__((address_space(3)))
; __device__ __forceinline__ float ex2(float x) { return __builtin_amdgcn_exp2f(x); }
; __device__ __forceinline__ float rcpf_(float x) { return __builtin_amdgcn_rcpf(x); }
; #define MFMA32(a, b, c) __builtin_amdgcn_mfma_f32_32x32x16_bf16((a), (b), (c), 0, 0, 0)
; __device__ __forceinline__ void lru_phase(const Ptrs& P, LAS unsigned char* lds, int G, int wave, int lane, int tid) {
;     ...
;     if ((int)blockIdx.x < 64 * NCHUNK) LRU_LOAD_RAW((int)blockIdx.x);
;     ...
;         const v4u xone_u = {hh == 0 ? 0x3F80u : 0u, 0u, 0u, 0u}; const bf16x8 xone = __builtin_bit_cast(bf16x8, xone_u);
; #pragma unroll
;         for (int mt = 0; mt < 3; ++mt) {
;             f32x16 gr, gi;
; #pragma unroll
;             for (int i = 0; i < 16; ++i) { gr[i] = 0.f; gi[i] = 0.f; }
;             const LAS bf16x8* wa = (const LAS bf16x8*)(lds + L_WGF) + (size_t)(mt * 6) * 64 + lane;
;             const LAS bf16x8* wb = (const LAS bf16x8*)(lds + L_WGF) + (size_t)((3 + mt) * 6) * 64 + lane;
; #pragma unroll
;             for (int s = 0; s < 5; ++s) { gr = MFMA32(wa[s * 64], xf[s], gr); gi = MFMA32(wb[s * 64], xf[s], gi); }
;             gr = MFMA32(wa[5 * 64], xone, gr); gi = MFMA32(wb[5 * 64], xone, gi);
;             __builtin_amdgcn_sched_barrier(0);
; #pragma unroll
;             for (int i4 = 0; i4 < 4; ++i4) { if (mt == 2 && i4 >= 2) continue;
;                 const int s = 2 * mt + (i4 >> 1), half = i4 & 1, ch0 = 16 * s + 8 * half + 4 * hh;
;                 const f32x4 ls2 = *(const LAS f32x4*)(par + 7 * LB + ch0);
;                 float A4[4], B4[4];
; #pragma unroll
;                 for (int q = 0; q < 4; ++q) { const int i = 4 * i4 + q;
;                     const float rg = rcpf_(1.0f + ex2(gr[i])), ig = rcpf_(1.0f + ex2(gi[i]));
;                     const float la2 = ls2[q] * rg, a = ex2(la2), xx = (2.0f * LN2) * la2;
;                     const float poly = -xx * (1.0f + xx * (0.5f + xx * ((1.0f / 6.0f) + xx * ((1.0f / 24.0f) + xx * (1.0f / 120.0f)))));
;                     const float om = (xx > -0.25f) ? poly : (1.0f - a * a);
.LBB0_304:
	s_or_b64 exec, exec, s[2:3]
	global_load_dwordx2 v[162:163], v[0:1], off offset:1024
	global_load_dwordx2 v[158:159], v[0:1], off offset:1536
	global_load_dwordx2 v[152:153], v[0:1], off offset:2048
	global_load_dwordx2 v[146:147], v[0:1], off offset:2560
	global_load_dwordx2 v[140:141], v[0:1], off offset:3072
	global_load_dwordx2 v[122:123], v[0:1], off offset:3584
	v_add_co_u32_e32 v2, vcc, s5, v0
	v_mov_b32_e32 v128, 0
	s_nop 0
	v_addc_co_u32_e32 v3, vcc, 0, v1, vcc
	global_load_dwordx2 v[174:175], v[0:1], off
	global_load_dwordx2 v[170:171], v[0:1], off offset:512
	global_load_dwordx2 v[120:121], v[2:3], off
	global_load_dwordx2 v[26:27], v[2:3], off offset:512
	v_mov_b32_e32 v0, 0x3f80
	v_cmp_gt_u32_e32 vcc, 32, v232
	v_mov_b32_e32 v1, v128
	s_mov_b64 s[2:3], 0x6000000
	v_cndmask_b32_e32 v32, 0, v0, vcc
	v_lshlrev_b32_e32 v0, 3, v232
	v_lshl_add_u64 v[0:1], s[54:55], 0, v[0:1]
	v_lshl_add_u64 v[130:131], v[0:1], 0, s[2:3]
	v_lshlrev_b32_e32 v0, 3, v184
	v_mov_b32_e32 v1, v128
	v_lshl_add_u64 v[0:1], s[54:55], 0, v[0:1]
	s_mov_b64 s[6:7], 0x130000
	s_add_u32 s16, s54, 0x8c00000
	v_lshrrev_b32_e32 v2, 5, v232
	s_mul_i32 s4, s63, 0x280
	v_lshl_add_u64 v[132:133], v[0:1], 0, s[6:7]
	v_and_or_b32 v1, v4, 31, v187
	s_addc_u32 s17, s55, 0
	v_lshlrev_b32_e32 v233, 4, v2
	s_add_i32 s27, s4, 0
	s_movk_i32 s4, 0x50
	s_mul_i32 s6, s63, 0xfffffec0
	v_lshlrev_b32_e32 v0, 3, v2
	v_lshlrev_b32_e32 v2, 3, v1
	v_mov_b32_e32 v3, v128
	v_add_u32_e32 v234, 0, v233
	v_mov_b32_e32 v33, v128
	v_mov_b32_e32 v34, v128
	v_mov_b32_e32 v35, v128
	v_cmp_eq_u32_e64 s[2:3], 31, v185
	v_add_u32_e32 v235, s26, v4
	v_cmp_gt_u32_e64 s[4:5], s4, v184
	v_lshl_add_u32 v236, v184, 2, 0
	s_add_i32 s28, s27, s6
	v_lshl_add_u32 v237, v232, 4, 0
	v_lshl_add_u64 v[134:135], s[10:11], 0, v[2:3]
	v_mov_b32_e32 v238, 0x3d2aaaab
	v_mov_b32_e32 v240, 1.0
	v_mov_b32_e32 v242, 0x3fb17218
	v_mov_b32_e32 v244, 0x3c088889
	v_mov_b32_e32 v246, 0x3e2aaaab
	v_mov_b32_e32 v248, 0.5
	s_mov_b32 s29, 0xbe800000
	s_mov_b32 s15, 1
	v_mov_b32_e32 v137, 1
	s_movk_i32 s30, 0xa00
	v_lshlrev_b32_e32 v138, 1, v0
	v_mov_b32_e32 v239, 0x280
	s_mov_b32 s20, s33
	s_branch .LBB0_308

; #define LAS __attribute__((address_space(3)))
; __device__ __forceinline__ unsigned pk2(float lo, float hi) { f32x2_t v = {lo, hi}; bf16x2_t b = __builtin_convertvector(v, bf16x2_t); return __builtin_bit_cast(unsigned, b); }
; __device__ __forceinline__ float bflo(unsigned u) { return __uint_as_float(u << 16); }
; __device__ __forceinline__ float bfhi(unsigned u) { return __uint_as_float(u & 0xffff0000u); }
; __device__ __forceinline__ void lru_phase(const Ptrs& P, LAS unsigned char* lds, int G, int wave, int lane, int tid) {
;     ...
;         float xc[5][2][4]; bf16x8 xf[5];
;         {
;           __builtin_amdgcn_sched_barrier(0);
; #pragma unroll
;           for (int s = 0; s < 5; ++s) { unsigned pkd[4];
; #pragma unroll
;               for (int half = 0; half < 2; ++half) { const int ch0 = 16 * s + 8 * half;
;                   const f32x4 cb = *(const LAS f32x4*)(par + 4 * LB + ch0 + 4 * hh);
;                   float a0 = cb[0], a1 = cb[1], a2 = cb[2], a3 = cb[3];
; #pragma unroll
;                   for (int tap = 0; tap < 4; ++tap) { const v2u rw = raw[s * 2 + half][tap];
;                       const f32x4 cw = *(const LAS f32x4*)(par + tap * LB + ch0 + 4 * hh);
;                       float c0 = cw[0], c1 = cw[1], c2 = cw[2], c3 = cw[3]; asm("" : "+v"(c0), "+v"(c1), "+v"(c2), "+v"(c3));
;                       a0 = __builtin_fmaf(c0, bflo(rw.x), a0); a1 = __builtin_fmaf(c1, bfhi(rw.x), a1); a2 = __builtin_fmaf(c2, bflo(rw.y), a2); a3 = __builtin_fmaf(c3, bfhi(rw.y), a3); }
;                   asm volatile("" : "+v"(a0), "+v"(a1), "+v"(a2), "+v"(a3));
;                   xc[s][half][0] = a0; xc[s][half][1] = a1; xc[s][half][2] = a2; xc[s][half][3] = a3;
;                   pkd[2 * half] = pk2(a0, a1); pkd[2 * half + 1] = pk2(a2, a3); __builtin_amdgcn_sched_barrier(0); }
;               v4u t = {pkd[0], pkd[1], pkd[2], pkd[3]}; xf[s] = __builtin_bit_cast(bf16x8, t); __builtin_amdgcn_sched_barrier(0); } }
.LBB0_308:
	s_ashr_i32 s35, s20, 6
	s_lshl_b32 s34, s35, 8
	s_bfe_u32 s31, s20, 0x20004
	s_add_i32 s34, s34, s26
	ds_read_b128 v[0:3], v234 offset:36864
	ds_read_b128 v[48:51], v234 offset:38144
	ds_read_b128 v[4:7], v234 offset:37184
	s_waitcnt vmcnt(33)
	v_lshlrev_b32_e32 v8, 16, v36
	s_waitcnt lgkmcnt(2)
	s_waitcnt lgkmcnt(1)
	v_fma_f32 v45, v0, v8, v48
	v_and_b32_e32 v0, 0xffff0000, v36
	v_fma_f32 v46, v1, v0, v49
	v_lshlrev_b32_e32 v0, 16, v37
	v_fma_f32 v50, v2, v0, v50
	v_and_b32_e32 v0, 0xffff0000, v37
	v_fmac_f32_e32 v51, v3, v0
	s_waitcnt lgkmcnt(0)
	v_mov_b32_e32 v0, v5
	v_mov_b32_e32 v5, v7
	v_mov_b32_e32 v1, v4
	s_waitcnt vmcnt(23)
	v_lshlrev_b32_e32 v2, 16, v168
	v_lshlrev_b32_e32 v4, 16, v169
	v_fmac_f32_e32 v45, v1, v2
	v_and_b32_e32 v1, 0xffff0000, v168
	v_fmac_f32_e32 v50, v6, v4
	v_and_b32_e32 v4, 0xffff0000, v169
	v_fmac_f32_e32 v46, v0, v1
	ds_read_b128 v[0:3], v234 offset:37504
	v_fmac_f32_e32 v51, v5, v4
	ds_read_b128 v[4:7], v234 offset:37824
	s_waitcnt lgkmcnt(1)
	s_waitcnt vmcnt(13)
	v_lshlrev_b32_e32 v8, 16, v172
	v_fmac_f32_e32 v45, v0, v8
	v_and_b32_e32 v0, 0xffff0000, v172
	v_fmac_f32_e32 v46, v1, v0
	v_lshlrev_b32_e32 v0, 16, v173
	v_fmac_f32_e32 v50, v2, v0
	v_and_b32_e32 v0, 0xffff0000, v173
	v_fmac_f32_e32 v51, v3, v0
	s_waitcnt lgkmcnt(0)
	v_mov_b32_e32 v0, v6
	v_mov_b32_e32 v1, v5
	v_mov_b32_e32 v2, v7
	s_waitcnt vmcnt(3)
	v_lshlrev_b32_e32 v3, 16, v174
	s_nop 0
	v_fmac_f32_e32 v45, v4, v3
	v_and_b32_e32 v3, 0xffff0000, v174
	v_fmac_f32_e32 v46, v1, v3
	v_lshlrev_b32_e32 v1, 16, v175
	v_fmac_f32_e32 v50, v0, v1
	v_and_b32_e32 v0, 0xffff0000, v175
	v_fmac_f32_e32 v51, v2, v0
	s_nop 0
	v_cvt_pk_bf16_f32 v36, v45, v46
	v_cvt_pk_bf16_f32 v37, v50, v51
	ds_read_b128 v[0:3], v234 offset:36896
	ds_read_b128 v[56:59], v234 offset:38176
	ds_read_b128 v[4:7], v234 offset:37216
	v_lshlrev_b32_e32 v8, 16, v38
	s_waitcnt lgkmcnt(2)
	s_waitcnt lgkmcnt(1)
	v_fma_f32 v53, v0, v8, v56
	v_and_b32_e32 v0, 0xffff0000, v38
	v_fma_f32 v54, v1, v0, v57
	v_lshlrev_b32_e32 v0, 16, v39
	v_fma_f32 v58, v2, v0, v58
	v_and_b32_e32 v0, 0xffff0000, v39
	v_fmac_f32_e32 v59, v3, v0
	s_waitcnt lgkmcnt(0)
	v_mov_b32_e32 v0, v5
	v_mov_b32_e32 v5, v7
	v_lshlrev_b32_e32 v1, 16, v164
	v_fmac_f32_e32 v53, v4, v1
	v_lshlrev_b32_e32 v4, 16, v165
	v_and_b32_e32 v1, 0xffff0000, v164
	v_fmac_f32_e32 v58, v6, v4
	v_and_b32_e32 v4, 0xffff0000, v165
	v_fmac_f32_e32 v54, v0, v1
	ds_read_b128 v[0:3], v234 offset:37536
	v_fmac_f32_e32 v59, v5, v4
	ds_read_b128 v[4:7], v234 offset:37856
	s_waitcnt lgkmcnt(1)
	v_lshlrev_b32_e32 v8, 16, v166
	v_fmac_f32_e32 v53, v0, v8
	v_and_b32_e32 v0, 0xffff0000, v166
	v_fmac_f32_e32 v54, v1, v0
	v_lshlrev_b32_e32 v0, 16, v167
	v_fmac_f32_e32 v58, v2, v0
	v_and_b32_e32 v0, 0xffff0000, v167
	v_fmac_f32_e32 v59, v3, v0
	s_waitcnt lgkmcnt(0)
	v_mov_b32_e32 v0, v4
	v_mov_b32_e32 v1, v6
	v_mov_b32_e32 v2, v5
	s_waitcnt vmcnt(2)
	v_lshlrev_b32_e32 v3, 16, v170
	v_fmac_f32_e32 v53, v0, v3
	v_and_b32_e32 v0, 0xffff0000, v170
	v_fmac_f32_e32 v54, v2, v0
	v_lshlrev_b32_e32 v0, 16, v171
	v_fmac_f32_e32 v58, v1, v0
	v_and_b32_e32 v0, 0xffff0000, v171
	v_fmac_f32_e32 v59, v7, v0
	s_nop 0
	v_cvt_pk_bf16_f32 v38, v53, v54
	v_cvt_pk_bf16_f32 v39, v58, v59
	ds_read_b128 v[0:3], v234 offset:36928
	ds_read_b128 v[64:67], v234 offset:38208
	ds_read_b128 v[4:7], v234 offset:37248
	v_lshlrev_b32_e32 v8, 16, v40
	s_waitcnt lgkmcnt(2)
	s_waitcnt lgkmcnt(1)
	v_fma_f32 v61, v0, v8, v64
	v_and_b32_e32 v0, 0xffff0000, v40
	v_fma_f32 v62, v1, v0, v65
	v_lshlrev_b32_e32 v0, 16, v41
	v_fma_f32 v66, v2, v0, v66
	v_and_b32_e32 v0, 0xffff0000, v41
	v_fmac_f32_e32 v67, v3, v0
	s_waitcnt lgkmcnt(0)
	v_mov_b32_e32 v0, v5
	v_mov_b32_e32 v5, v7
	v_lshlrev_b32_e32 v1, 16, v156
	v_fmac_f32_e32 v61, v4, v1
	v_lshlrev_b32_e32 v4, 16, v157
	v_and_b32_e32 v1, 0xffff0000, v156
	v_fmac_f32_e32 v66, v6, v4
	v_and_b32_e32 v4, 0xffff0000, v157
	v_fmac_f32_e32 v62, v0, v1
	ds_read_b128 v[0:3], v234 offset:37568
	v_fmac_f32_e32 v67, v5, v4
	ds_read_b128 v[4:7], v234 offset:37888
	s_waitcnt lgkmcnt(1)
	v_lshlrev_b32_e32 v8, 16, v160
	v_fmac_f32_e32 v61, v0, v8
	v_and_b32_e32 v0, 0xffff0000, v160
	v_fmac_f32_e32 v62, v1, v0
	v_lshlrev_b32_e32 v0, 16, v161
	v_fmac_f32_e32 v66, v2, v0
	v_and_b32_e32 v0, 0xffff0000, v161
	v_fmac_f32_e32 v67, v3, v0
	s_waitcnt lgkmcnt(0)
	v_mov_b32_e32 v0, v7
	v_mov_b32_e32 v1, v4
	v_mov_b32_e32 v2, v6
	v_lshlrev_b32_e32 v3, 16, v162
	v_fmac_f32_e32 v61, v1, v3
	v_and_b32_e32 v1, 0xffff0000, v162
	v_fmac_f32_e32 v62, v5, v1
	v_lshlrev_b32_e32 v1, 16, v163
	v_fmac_f32_e32 v66, v2, v1
	v_and_b32_e32 v1, 0xffff0000, v163
	v_fmac_f32_e32 v67, v0, v1
	s_nop 0
	v_cvt_pk_bf16_f32 v40, v61, v62
	v_cvt_pk_bf16_f32 v41, v66, v67
	ds_read_b128 v[0:3], v234 offset:36960
	ds_read_b128 v[72:75], v234 offset:38240
	ds_read_b128 v[4:7], v234 offset:37280
	v_lshlrev_b32_e32 v8, 16, v42
	s_waitcnt lgkmcnt(2)
	s_waitcnt lgkmcnt(1)
	v_fma_f32 v69, v0, v8, v72
	v_and_b32_e32 v0, 0xffff0000, v42
	v_fma_f32 v70, v1, v0, v73
	v_lshlrev_b32_e32 v0, 16, v43
	v_fma_f32 v74, v2, v0, v74
	v_and_b32_e32 v0, 0xffff0000, v43
	v_fmac_f32_e32 v75, v3, v0
	s_waitcnt lgkmcnt(0)
	v_mov_b32_e32 v0, v4
	v_mov_b32_e32 v4, v6
	v_mov_b32_e32 v1, v5
	v_lshlrev_b32_e32 v2, 16, v150
	v_lshlrev_b32_e32 v5, 16, v151
	v_fmac_f32_e32 v69, v0, v2
	v_and_b32_e32 v0, 0xffff0000, v150
	v_fmac_f32_e32 v74, v4, v5
	v_and_b32_e32 v4, 0xffff0000, v151
	v_fmac_f32_e32 v70, v1, v0
	ds_read_b128 v[0:3], v234 offset:37600
	v_fmac_f32_e32 v75, v7, v4
	ds_read_b128 v[4:7], v234 offset:37920
	s_waitcnt lgkmcnt(1)
; #define LAS __attribute__((address_space(3)))
; __device__ __forceinline__ unsigned pk2(float lo, float hi) { f32x2_t v = {lo, hi}; bf16x2_t b = __builtin_convertvector(v, bf16x2_t); return __builtin_bit_cast(unsigned, b); }
; __device__ __forceinline__ float bflo(unsigned u) { return __uint_as_float(u << 16); }
; __device__ __forceinline__ float bfhi(unsigned u) { return __uint_as_float(u & 0xffff0000u); }
; __device__ __forceinline__ void lru_phase(const Ptrs& P, LAS unsigned char* lds, int G, int wave, int lane, int tid) {
;     ...
;           for (int s = 0; s < 5; ++s) { unsigned pkd[4];
; #pragma unroll
;               for (int half = 0; half < 2; ++half) { const int ch0 = 16 * s + 8 * half;
;                   const f32x4 cb = *(const LAS f32x4*)(par + 4 * LB + ch0 + 4 * hh);
;                   float a0 = cb[0], a1 = cb[1], a2 = cb[2], a3 = cb[3];
; #pragma unroll
;                   for (int tap = 0; tap < 4; ++tap) { const v2u rw = raw[s * 2 + half][tap];
;                       const f32x4 cw = *(const LAS f32x4*)(par + tap * LB + ch0 + 4 * hh);
;                       float c0 = cw[0], c1 = cw[1], c2 = cw[2], c3 = cw[3]; asm("" : "+v"(c0), "+v"(c1), "+v"(c2), "+v"(c3));
;                       a0 = __builtin_fmaf(c0, bflo(rw.x), a0); a1 = __builtin_fmaf(c1, bfhi(rw.x), a1); a2 = __builtin_fmaf(c2, bflo(rw.y), a2); a3 = __builtin_fmaf(c3, bfhi(rw.y), a3); }
;                   asm volatile("" : "+v"(a0), "+v"(a1), "+v"(a2), "+v"(a3));
;                   xc[s][half][0] = a0; xc[s][half][1] = a1; xc[s][half][2] = a2; xc[s][half][3] = a3;
;                   pkd[2 * half] = pk2(a0, a1); pkd[2 * half + 1] = pk2(a2, a3); __builtin_amdgcn_sched_barrier(0); }
;               v4u t = {pkd[0], pkd[1], pkd[2], pkd[3]}; xf[s] = __builtin_bit_cast(bf16x8, t); __builtin_amdgcn_sched_barrier(0); } }
	v_lshlrev_b32_e32 v8, 16, v154
	v_fmac_f32_e32 v69, v0, v8
	v_and_b32_e32 v0, 0xffff0000, v154
	v_fmac_f32_e32 v70, v1, v0
	v_lshlrev_b32_e32 v0, 16, v155
	v_fmac_f32_e32 v74, v2, v0
	v_and_b32_e32 v0, 0xffff0000, v155
	v_fmac_f32_e32 v75, v3, v0
	s_waitcnt lgkmcnt(0)
	v_mov_b32_e32 v0, v7
	v_mov_b32_e32 v1, v4
	v_mov_b32_e32 v2, v6
	v_lshlrev_b32_e32 v3, 16, v158
	v_fmac_f32_e32 v69, v1, v3
	v_and_b32_e32 v1, 0xffff0000, v158
	v_fmac_f32_e32 v70, v5, v1
	v_lshlrev_b32_e32 v1, 16, v159
	v_fmac_f32_e32 v74, v2, v1
	v_and_b32_e32 v1, 0xffff0000, v159
	v_fmac_f32_e32 v75, v0, v1
	s_nop 0
	v_cvt_pk_bf16_f32 v42, v69, v70
	v_cvt_pk_bf16_f32 v43, v74, v75
	ds_read_b128 v[0:3], v234 offset:36992
	ds_read_b128 v[84:87], v234 offset:38272
	ds_read_b128 v[4:7], v234 offset:37312
	v_lshlrev_b32_e32 v8, 16, v76
	s_waitcnt lgkmcnt(2)
	s_waitcnt lgkmcnt(1)
	v_fma_f32 v81, v0, v8, v84
	v_and_b32_e32 v0, 0xffff0000, v76
	v_fma_f32 v82, v1, v0, v85
	v_lshlrev_b32_e32 v0, 16, v77
	v_fma_f32 v86, v2, v0, v86
	v_and_b32_e32 v0, 0xffff0000, v77
	v_fmac_f32_e32 v87, v3, v0
	s_waitcnt lgkmcnt(0)
	v_mov_b32_e32 v0, v4
	v_mov_b32_e32 v4, v6
	v_lshlrev_b32_e32 v1, 16, v144
	v_fmac_f32_e32 v81, v0, v1
	v_and_b32_e32 v0, 0xffff0000, v144
	v_fmac_f32_e32 v82, v5, v0
	v_lshlrev_b32_e32 v5, 16, v145
	v_fmac_f32_e32 v86, v4, v5
	v_and_b32_e32 v4, 0xffff0000, v145
	ds_read_b128 v[0:3], v234 offset:37632
	v_fmac_f32_e32 v87, v7, v4
	ds_read_b128 v[4:7], v234 offset:37952
	s_waitcnt lgkmcnt(1)
	v_lshlrev_b32_e32 v8, 16, v148
	v_fmac_f32_e32 v81, v0, v8
	v_and_b32_e32 v0, 0xffff0000, v148
	v_fmac_f32_e32 v82, v1, v0
	v_lshlrev_b32_e32 v0, 16, v149
	v_fmac_f32_e32 v86, v2, v0
	v_and_b32_e32 v0, 0xffff0000, v149
	v_fmac_f32_e32 v87, v3, v0
	s_waitcnt lgkmcnt(0)
	v_mov_b32_e32 v0, v7
	v_mov_b32_e32 v1, v4
	v_mov_b32_e32 v2, v6
	v_lshlrev_b32_e32 v3, 16, v152
	v_fmac_f32_e32 v81, v1, v3
	v_and_b32_e32 v1, 0xffff0000, v152
	v_fmac_f32_e32 v82, v5, v1
	v_lshlrev_b32_e32 v1, 16, v153
	v_fmac_f32_e32 v86, v2, v1
	v_and_b32_e32 v1, 0xffff0000, v153
	v_fmac_f32_e32 v87, v0, v1
	s_nop 0
	v_cvt_pk_bf16_f32 v76, v81, v82
	v_cvt_pk_bf16_f32 v77, v86, v87
	ds_read_b128 v[0:3], v234 offset:37024
	ds_read_b128 v[92:95], v234 offset:38304
	ds_read_b128 v[4:7], v234 offset:37344
	v_lshlrev_b32_e32 v8, 16, v78
	s_waitcnt lgkmcnt(2)
	s_waitcnt lgkmcnt(1)
	v_fma_f32 v89, v0, v8, v92
	v_and_b32_e32 v0, 0xffff0000, v78
	v_fma_f32 v90, v1, v0, v93
	v_lshlrev_b32_e32 v0, 16, v79
	v_fma_f32 v94, v2, v0, v94
	v_and_b32_e32 v0, 0xffff0000, v79
	v_fmac_f32_e32 v95, v3, v0
	s_waitcnt lgkmcnt(0)
	v_mov_b32_e32 v0, v4
	v_mov_b32_e32 v4, v6
	v_lshlrev_b32_e32 v1, 16, v126
	v_fmac_f32_e32 v89, v0, v1
	v_and_b32_e32 v0, 0xffff0000, v126
	v_fmac_f32_e32 v90, v5, v0
	v_lshlrev_b32_e32 v5, 16, v127
	v_fmac_f32_e32 v94, v4, v5
	v_and_b32_e32 v4, 0xffff0000, v127
	ds_read_b128 v[0:3], v234 offset:37664
	v_fmac_f32_e32 v95, v7, v4
	ds_read_b128 v[4:7], v234 offset:37984
	s_waitcnt lgkmcnt(1)
	v_lshlrev_b32_e32 v8, 16, v142
	v_fmac_f32_e32 v89, v0, v8
	v_and_b32_e32 v0, 0xffff0000, v142
	v_fmac_f32_e32 v90, v1, v0
	v_lshlrev_b32_e32 v0, 16, v143
	v_fmac_f32_e32 v94, v2, v0
	v_and_b32_e32 v0, 0xffff0000, v143
	v_fmac_f32_e32 v95, v3, v0
	s_waitcnt lgkmcnt(0)
	v_mov_b32_e32 v0, v7
	v_mov_b32_e32 v1, v4
	v_mov_b32_e32 v2, v6
	v_lshlrev_b32_e32 v3, 16, v146
	v_fmac_f32_e32 v89, v1, v3
	v_and_b32_e32 v1, 0xffff0000, v146
	v_fmac_f32_e32 v90, v5, v1
	v_lshlrev_b32_e32 v1, 16, v147
	v_fmac_f32_e32 v94, v2, v1
	v_and_b32_e32 v1, 0xffff0000, v147
	v_fmac_f32_e32 v95, v0, v1
	s_nop 0
	v_cvt_pk_bf16_f32 v78, v89, v90
	v_cvt_pk_bf16_f32 v79, v94, v95
	ds_read_b128 v[0:3], v234 offset:37056
	ds_read_b128 v[100:103], v234 offset:38336
	ds_read_b128 v[4:7], v234 offset:37376
	v_lshlrev_b32_e32 v8, 16, v112
	s_waitcnt lgkmcnt(2)
	s_waitcnt lgkmcnt(1)
	v_fma_f32 v97, v0, v8, v100
	v_and_b32_e32 v0, 0xffff0000, v112
	v_fma_f32 v98, v1, v0, v101
	v_lshlrev_b32_e32 v0, 16, v113
	v_fma_f32 v102, v2, v0, v102
	v_and_b32_e32 v0, 0xffff0000, v113
	v_fmac_f32_e32 v103, v3, v0
	s_waitcnt lgkmcnt(0)
	v_mov_b32_e32 v0, v4
	v_mov_b32_e32 v4, v6
	v_lshlrev_b32_e32 v1, 16, v118
	v_fmac_f32_e32 v97, v0, v1
	v_and_b32_e32 v0, 0xffff0000, v118
	v_fmac_f32_e32 v98, v5, v0
	v_lshlrev_b32_e32 v5, 16, v119
	v_fmac_f32_e32 v102, v4, v5
	v_and_b32_e32 v4, 0xffff0000, v119
	ds_read_b128 v[0:3], v234 offset:37696
	v_fmac_f32_e32 v103, v7, v4
	ds_read_b128 v[4:7], v234 offset:38016
	s_waitcnt lgkmcnt(1)
	v_lshlrev_b32_e32 v8, 16, v124
	v_fmac_f32_e32 v97, v0, v8
	v_and_b32_e32 v0, 0xffff0000, v124
	v_fmac_f32_e32 v98, v1, v0
	v_lshlrev_b32_e32 v0, 16, v125
	v_fmac_f32_e32 v102, v2, v0
	v_and_b32_e32 v0, 0xffff0000, v125
	v_fmac_f32_e32 v103, v3, v0
	s_waitcnt lgkmcnt(0)
	v_mov_b32_e32 v0, v5
	v_mov_b32_e32 v1, v7
	v_mov_b32_e32 v2, v4
	v_lshlrev_b32_e32 v3, 16, v140
	v_fmac_f32_e32 v97, v2, v3
	v_and_b32_e32 v2, 0xffff0000, v140
	v_fmac_f32_e32 v98, v0, v2
	v_lshlrev_b32_e32 v0, 16, v141
	v_fmac_f32_e32 v102, v6, v0
	v_and_b32_e32 v0, 0xffff0000, v141
	v_fmac_f32_e32 v103, v1, v0
	s_nop 0
	v_cvt_pk_bf16_f32 v112, v97, v98
	v_cvt_pk_bf16_f32 v113, v102, v103
	ds_read_b128 v[0:3], v234 offset:37088
	ds_read_b128 v[108:111], v234 offset:38368
	ds_read_b128 v[4:7], v234 offset:37408
	v_lshlrev_b32_e32 v8, 16, v28
	s_waitcnt lgkmcnt(2)
	s_waitcnt lgkmcnt(1)
	v_fma_f32 v105, v0, v8, v108
	v_and_b32_e32 v0, 0xffff0000, v28
	v_fma_f32 v106, v1, v0, v109
	v_lshlrev_b32_e32 v0, 16, v29
	v_fma_f32 v110, v2, v0, v110
	v_and_b32_e32 v0, 0xffff0000, v29
	v_fmac_f32_e32 v111, v3, v0
	s_waitcnt lgkmcnt(0)
; #define LAS __attribute__((address_space(3)))
; __device__ __forceinline__ float bflo(unsigned u) { return __uint_as_float(u << 16); }
; __device__ __forceinline__ void lru_phase(const Ptrs& P, LAS unsigned char* lds, int G, int wave, int lane, int tid) {
;     ...
;           for (int s = 0; s < 5; ++s) { unsigned pkd[4];
; #pragma unroll
;               for (int half = 0; half < 2; ++half) { const int ch0 = 16 * s + 8 * half;
;                   const f32x4 cb = *(const LAS f32x4*)(par + 4 * LB + ch0 + 4 * hh);
;                   float a0 = cb[0], a1 = cb[1], a2 = cb[2], a3 = cb[3];
; #pragma unroll
;                   for (int tap = 0; tap < 4; ++tap) { const v2u rw = raw[s * 2 + half][tap];
;                       const f32x4 cw = *(const LAS f32x4*)(par + tap * LB + ch0 + 4 * hh);
;                       float c0 = cw[0], c1 = cw[1], c2 = cw[2], c3 = cw[3]; asm("" : "+v"(c0), "+v"(c1), "+v"(c2), "+v"(c3));
;                       a0 = __builtin_fmaf(c0, bflo(rw.x), a0); a1 = __builtin_fmaf(c1, bfhi(rw.x), a1); a2 = __builtin_fmaf(c2, bflo(rw.y), a2); a3 = __builtin_fmaf(c3, bfhi(rw.y), a3); }
;                   asm volatile("" : "+v"(a0), "+v"(a1), "+v"(a2), "+v"(a3));
;                   xc[s][half][0] = a0; xc[s][half][1] = a1; xc[s][half][2] = a2; xc[s][half][3] = a3;
;                   pkd[2 * half] = pk2(a0, a1); pkd[2 * half + 1] = pk2(a2, a3); __builtin_amdgcn_sched_barrier(0); }
;               v4u t = {pkd[0], pkd[1], pkd[2], pkd[3]}; xf[s] = __builtin_bit_cast(bf16x8, t); __builtin_amdgcn_sched_barrier(0); } }
;         float Av[5][2][4];
;         const v4u xone_u = {hh == 0 ? 0x3F80u : 0u, 0u, 0u, 0u}; const bf16x8 xone = __builtin_bit_cast(bf16x8, xone_u);
; #pragma unroll
;         for (int mt = 0; mt < 3; ++mt) {
;             f32x16 gr, gi;
; #pragma unroll
;             for (int i = 0; i < 16; ++i) { gr[i] = 0.f; gi[i] = 0.f; }
;             const LAS bf16x8* wa = (const LAS bf16x8*)(lds + L_WGF) + (size_t)(mt * 6) * 64 + lane;
;             const LAS bf16x8* wb = (const LAS bf16x8*)(lds + L_WGF) + (size_t)((3 + mt) * 6) * 64 + lane;
; #pragma unroll
;             for (int s = 0; s < 5; ++s) { gr = MFMA32(wa[s * 64], xf[s], gr); gi = MFMA32(wb[s * 64], xf[s], gi); }
;             gr = MFMA32(wa[5 * 64], xone, gr); gi = MFMA32(wb[5 * 64], xone, gi);
;             __builtin_amdgcn_sched_barrier(0);
	v_mov_b32_e32 v0, v4
	v_mov_b32_e32 v4, v6
	v_lshlrev_b32_e32 v1, 16, v114
	v_fmac_f32_e32 v105, v0, v1
	v_and_b32_e32 v0, 0xffff0000, v114
	v_fmac_f32_e32 v106, v5, v0
	v_lshlrev_b32_e32 v5, 16, v115
	v_fmac_f32_e32 v110, v4, v5
	v_and_b32_e32 v4, 0xffff0000, v115
	ds_read_b128 v[0:3], v234 offset:37728
	v_fmac_f32_e32 v111, v7, v4
	ds_read_b128 v[4:7], v234 offset:38048
	s_waitcnt lgkmcnt(1)
	v_lshlrev_b32_e32 v8, 16, v116
	v_fmac_f32_e32 v105, v0, v8
	v_and_b32_e32 v0, 0xffff0000, v116
	v_fmac_f32_e32 v106, v1, v0
	v_lshlrev_b32_e32 v0, 16, v117
	v_fmac_f32_e32 v110, v2, v0
	v_and_b32_e32 v0, 0xffff0000, v117
	v_fmac_f32_e32 v111, v3, v0
	s_waitcnt lgkmcnt(0)
	v_mov_b32_e32 v0, v6
	v_mov_b32_e32 v1, v5
	v_mov_b32_e32 v2, v7
	v_lshlrev_b32_e32 v3, 16, v122
	s_nop 0
	v_fmac_f32_e32 v105, v4, v3
	v_and_b32_e32 v3, 0xffff0000, v122
	v_fmac_f32_e32 v106, v1, v3
	v_lshlrev_b32_e32 v1, 16, v123
	v_fmac_f32_e32 v110, v0, v1
	v_and_b32_e32 v0, 0xffff0000, v123
	v_fmac_f32_e32 v111, v2, v0
	s_nop 0
	v_cvt_pk_bf16_f32 v114, v105, v106
	v_cvt_pk_bf16_f32 v115, v110, v111
	ds_read_b128 v[0:3], v234 offset:37120
	ds_read_b128 v[116:119], v234 offset:38400
	ds_read_b128 v[4:7], v234 offset:37440
	v_lshlrev_b32_e32 v8, 16, v20
	s_waitcnt lgkmcnt(2)
	s_waitcnt lgkmcnt(1)
	v_fma_f32 v136, v0, v8, v116
	v_and_b32_e32 v0, 0xffff0000, v20
	v_fma_f32 v129, v1, v0, v117
	v_lshlrev_b32_e32 v0, 16, v21
	v_fma_f32 v116, v2, v0, v118
	v_and_b32_e32 v0, 0xffff0000, v21
	v_fmac_f32_e32 v119, v3, v0
	s_waitcnt lgkmcnt(0)
	v_mov_b32_e32 v0, v5
	v_mov_b32_e32 v5, v7
	v_mov_b32_e32 v1, v4
	v_lshlrev_b32_e32 v2, 16, v24
	v_lshlrev_b32_e32 v4, 16, v25
	v_fmac_f32_e32 v136, v1, v2
	v_and_b32_e32 v1, 0xffff0000, v24
	v_fmac_f32_e32 v116, v6, v4
	v_and_b32_e32 v4, 0xffff0000, v25
	v_fmac_f32_e32 v129, v0, v1
	ds_read_b128 v[0:3], v234 offset:37760
	v_fmac_f32_e32 v119, v5, v4
	ds_read_b128 v[4:7], v234 offset:38080
	s_waitcnt lgkmcnt(1)
	v_lshlrev_b32_e32 v8, 16, v30
	v_fmac_f32_e32 v136, v0, v8
	v_and_b32_e32 v0, 0xffff0000, v30
	v_fmac_f32_e32 v129, v1, v0
	v_lshlrev_b32_e32 v0, 16, v31
	v_fmac_f32_e32 v116, v2, v0
	v_and_b32_e32 v0, 0xffff0000, v31
	v_fmac_f32_e32 v119, v3, v0
	s_waitcnt lgkmcnt(0)
	v_mov_b32_e32 v0, v6
	v_mov_b32_e32 v1, v5
	v_mov_b32_e32 v2, v7
	s_waitcnt vmcnt(1)
	v_lshlrev_b32_e32 v3, 16, v120
	s_nop 0
	v_fmac_f32_e32 v136, v4, v3
	v_and_b32_e32 v3, 0xffff0000, v120
	v_fmac_f32_e32 v129, v1, v3
	v_lshlrev_b32_e32 v1, 16, v121
	v_fmac_f32_e32 v116, v0, v1
	v_and_b32_e32 v0, 0xffff0000, v121
	v_fmac_f32_e32 v119, v2, v0
	s_nop 0
	v_cvt_pk_bf16_f32 v124, v136, v129
	v_cvt_pk_bf16_f32 v125, v116, v119
	ds_read_b128 v[0:3], v234 offset:37152
	ds_read_b128 v[120:123], v234 offset:38432
	ds_read_b128 v[4:7], v234 offset:37472
	v_lshlrev_b32_e32 v8, 16, v16
	s_waitcnt lgkmcnt(2)
	s_waitcnt lgkmcnt(1)
	v_fma_f32 v120, v0, v8, v120
	v_and_b32_e32 v0, 0xffff0000, v16
	v_fma_f32 v118, v1, v0, v121
	v_lshlrev_b32_e32 v0, 16, v17
	v_fma_f32 v117, v2, v0, v122
	v_and_b32_e32 v0, 0xffff0000, v17
	v_fmac_f32_e32 v123, v3, v0
	s_waitcnt lgkmcnt(0)
	v_mov_b32_e32 v0, v5
	v_mov_b32_e32 v5, v7
	v_lshlrev_b32_e32 v1, 16, v18
	v_fmac_f32_e32 v120, v4, v1
	v_lshlrev_b32_e32 v4, 16, v19
	v_and_b32_e32 v1, 0xffff0000, v18
	v_fmac_f32_e32 v117, v6, v4
	v_and_b32_e32 v4, 0xffff0000, v19
	v_fmac_f32_e32 v118, v0, v1
	ds_read_b128 v[0:3], v234 offset:37792
	v_fmac_f32_e32 v123, v5, v4
	ds_read_b128 v[4:7], v234 offset:38112
	s_waitcnt lgkmcnt(1)
	v_lshlrev_b32_e32 v8, 16, v22
	v_fmac_f32_e32 v120, v0, v8
	v_and_b32_e32 v0, 0xffff0000, v22
	v_fmac_f32_e32 v118, v1, v0
	v_lshlrev_b32_e32 v0, 16, v23
	v_fmac_f32_e32 v117, v2, v0
	v_and_b32_e32 v0, 0xffff0000, v23
	v_fmac_f32_e32 v123, v3, v0
	s_waitcnt lgkmcnt(0)
	v_mov_b32_e32 v0, v4
	v_mov_b32_e32 v1, v6
	v_mov_b32_e32 v2, v5
	s_waitcnt vmcnt(0)
	v_lshlrev_b32_e32 v3, 16, v26
	v_fmac_f32_e32 v120, v0, v3
	v_and_b32_e32 v0, 0xffff0000, v26
	v_fmac_f32_e32 v118, v2, v0
	v_lshlrev_b32_e32 v0, 16, v27
	v_fmac_f32_e32 v117, v1, v0
	v_and_b32_e32 v0, 0xffff0000, v27
	v_fmac_f32_e32 v123, v7, v0
	s_nop 0
	v_cvt_pk_bf16_f32 v126, v120, v118
	v_cvt_pk_bf16_f32 v127, v117, v123
	ds_read_b128 v[0:3], v237
	ds_read_b128 v[140:143], v237 offset:1024
	ds_read_b128 v[16:19], v237 offset:18432
	ds_read_b128 v[144:147], v237 offset:19456
	s_waitcnt lgkmcnt(3)
	v_mfma_f32_32x32x16_bf16 v[0:15], v[0:3], v[36:39], 0
	s_waitcnt lgkmcnt(1)
	v_mfma_f32_32x32x16_bf16 v[16:31], v[16:19], v[36:39], 0
	v_mfma_f32_32x32x16_bf16 v[0:15], v[140:143], v[40:43], v[0:15]
	s_waitcnt lgkmcnt(0)
	v_mfma_f32_32x32x16_bf16 v[16:31], v[144:147], v[40:43], v[16:31]
	ds_read_b128 v[140:143], v237 offset:2048
	ds_read_b128 v[144:147], v237 offset:3072
	s_waitcnt lgkmcnt(1)
	v_mfma_f32_32x32x16_bf16 v[0:15], v[140:143], v[76:79], v[0:15]
	ds_read_b128 v[140:143], v237 offset:20480
	ds_read_b128 v[148:151], v237 offset:21504
	s_waitcnt lgkmcnt(1)
	v_mfma_f32_32x32x16_bf16 v[16:31], v[140:143], v[76:79], v[16:31]
	v_mfma_f32_32x32x16_bf16 v[0:15], v[144:147], v[112:115], v[0:15]
	ds_read_b128 v[140:143], v237 offset:4096
	ds_read_b128 v[144:147], v237 offset:5120
	s_waitcnt lgkmcnt(2)
	v_mfma_f32_32x32x16_bf16 v[16:31], v[148:151], v[112:115], v[16:31]
	s_waitcnt lgkmcnt(1)
	v_mfma_f32_32x32x16_bf16 v[0:15], v[140:143], v[124:127], v[0:15]
	ds_read_b128 v[140:143], v237 offset:22528
	ds_read_b128 v[148:151], v237 offset:23552
	s_waitcnt lgkmcnt(1)
	v_mfma_f32_32x32x16_bf16 v[16:31], v[140:143], v[124:127], v[16:31]
	v_mfma_f32_32x32x16_bf16 v[0:15], v[144:147], v[32:35], v[0:15]
	s_waitcnt lgkmcnt(0)
; #define LAS __attribute__((address_space(3)))
; __device__ __forceinline__ float ex2(float x) { return __builtin_amdgcn_exp2f(x); }
; __device__ __forceinline__ float rcpf_(float x) { return __builtin_amdgcn_rcpf(x); }
; __device__ __forceinline__ void lru_phase(const Ptrs& P, LAS unsigned char* lds, int G, int wave, int lane, int tid) {
;     ...
;             for (int i4 = 0; i4 < 4; ++i4) { if (mt == 2 && i4 >= 2) continue;
;                 const int s = 2 * mt + (i4 >> 1), half = i4 & 1, ch0 = 16 * s + 8 * half + 4 * hh;
;                 const f32x4 ls2 = *(const LAS f32x4*)(par + 7 * LB + ch0);
;                 float A4[4], B4[4];
; #pragma unroll
;                 for (int q = 0; q < 4; ++q) { const int i = 4 * i4 + q;
;                     const float rg = rcpf_(1.0f + ex2(gr[i])), ig = rcpf_(1.0f + ex2(gi[i]));
;                     const float la2 = ls2[q] * rg, a = ex2(la2), xx = (2.0f * LN2) * la2;
;                     const float poly = -xx * (1.0f + xx * (0.5f + xx * ((1.0f / 6.0f) + xx * ((1.0f / 24.0f) + xx * (1.0f / 120.0f)))));
;                     const float om = (xx > -0.25f) ? poly : (1.0f - a * a);
;                     A4[q] = a; B4[q] = __builtin_amdgcn_sqrtf(om) * (ig * xc[s][half][q]); }
;                 asm volatile("s_nop 1\n\t"
;                     LRU_DPP4("row_shr:1 row_mask:0xf bank_mask:0xf") LRU_DPP4("row_shr:2 row_mask:0xf bank_mask:0xf") LRU_DPP4("row_shr:4 row_mask:0xf bank_mask:0xf")
;                     LRU_DPP4("row_shr:8 row_mask:0xf bank_mask:0xf") LRU_DPP4("row_bcast:15 row_mask:0xa bank_mask:0xf")
;                     : "+v"(A4[0]), "+v"(A4[1]), "+v"(A4[2]), "+v"(A4[3]), "+v"(B4[0]), "+v"(B4[1]), "+v"(B4[2]), "+v"(B4[3]));
; #pragma unroll
;                 for (int q = 0; q < 4; ++q) { Av[s][half][q] = A4[q]; xc[s][half][q] = B4[q]; }
;                 __builtin_amdgcn_sched_barrier(0); }
	v_mfma_f32_32x32x16_bf16 v[16:31], v[148:151], v[32:35], v[16:31]
	s_nop 9
	ds_read_b128 v[140:143], v234 offset:39104
	v_exp_f32_e32 v0, v0
	v_exp_f32_e32 v1, v1
	v_exp_f32_e32 v2, v2
	v_exp_f32_e32 v3, v3
	v_exp_f32_e32 v16, v16
	v_exp_f32_e32 v17, v17
	v_exp_f32_e32 v18, v18
	v_exp_f32_e32 v19, v19
	v_pk_add_f32 v[0:1], v[0:1], v[240:241] op_sel_hi:[1,0]
	v_pk_add_f32 v[2:3], v[2:3], v[240:241] op_sel_hi:[1,0]
	v_pk_add_f32 v[16:17], v[16:17], v[240:241] op_sel_hi:[1,0]
	v_pk_add_f32 v[18:19], v[18:19], v[240:241] op_sel_hi:[1,0]
	v_rcp_f32_e32 v0, v0
	v_rcp_f32_e32 v1, v1
	v_rcp_f32_e32 v2, v2
	v_rcp_f32_e32 v3, v3
	v_rcp_f32_e32 v16, v16
	v_rcp_f32_e32 v17, v17
	v_rcp_f32_e32 v18, v18
	v_rcp_f32_e32 v19, v19
	v_mul_f32_e32 v200, v45, v16
	v_mul_f32_e32 v201, v46, v17
	v_mul_f32_e32 v202, v50, v18
	v_mul_f32_e32 v203, v51, v19
	s_waitcnt lgkmcnt(0)
	v_pk_mul_f32 v[0:1], v[0:1], v[140:141]
	v_pk_mul_f32 v[2:3], v[2:3], v[142:143]
	v_pk_mul_f32 v[204:205], v[0:1], v[242:243] op_sel_hi:[1,0]
	v_pk_mul_f32 v[206:207], v[2:3], v[242:243] op_sel_hi:[1,0]
	v_exp_f32_e32 v44, v0
	v_exp_f32_e32 v45, v1
	v_exp_f32_e32 v46, v2
	v_exp_f32_e32 v47, v3
	v_pk_fma_f32 v[208:209], v[204:205], v[244:245], v[238:239] op_sel_hi:[1,0,0]
	v_pk_fma_f32 v[210:211], v[206:207], v[244:245], v[238:239] op_sel_hi:[1,0,0]
	v_pk_fma_f32 v[208:209], v[204:205], v[208:209], v[246:247] op_sel_hi:[1,1,0]
	v_pk_fma_f32 v[210:211], v[206:207], v[210:211], v[246:247] op_sel_hi:[1,1,0]
	v_pk_fma_f32 v[208:209], v[204:205], v[208:209], v[248:249] op_sel_hi:[1,1,0]
	v_pk_fma_f32 v[210:211], v[206:207], v[210:211], v[248:249] op_sel_hi:[1,1,0]
	v_pk_fma_f32 v[208:209], v[204:205], v[208:209], v[240:241] op_sel_hi:[1,1,0]
	v_pk_fma_f32 v[210:211], v[206:207], v[210:211], v[240:241] op_sel_hi:[1,1,0]
	v_pk_mul_f32 v[208:209], v[208:209], v[204:205] neg_lo:[0,1] neg_hi:[0,1]
	v_pk_mul_f32 v[210:211], v[210:211], v[206:207] neg_lo:[0,1] neg_hi:[0,1]
	v_pk_fma_f32 v[212:213], v[44:45], v[44:45], v[240:241] op_sel_hi:[1,1,0] neg_lo:[1,0,0] neg_hi:[1,0,0]
	v_pk_fma_f32 v[214:215], v[46:47], v[46:47], v[240:241] op_sel_hi:[1,1,0] neg_lo:[1,0,0] neg_hi:[1,0,0]
	v_cmp_lt_f32_e64 s[70:71], s29, v204
	v_cmp_lt_f32_e64 s[72:73], s29, v205
	v_cmp_lt_f32_e64 s[74:75], s29, v206
	v_cmp_lt_f32_e64 s[76:77], s29, v207
	v_cndmask_b32_e64 v212, v212, v208, s[70:71]
	v_cndmask_b32_e64 v213, v213, v209, s[72:73]
	v_cndmask_b32_e64 v214, v214, v210, s[74:75]
	v_cndmask_b32_e64 v215, v215, v211, s[76:77]
	v_sqrt_f32_e32 v212, v212
	v_sqrt_f32_e32 v213, v213
	v_sqrt_f32_e32 v214, v214
	v_sqrt_f32_e32 v215, v215
	v_pk_mul_f32 v[48:49], v[200:201], v[212:213]
	v_pk_mul_f32 v[50:51], v[202:203], v[214:215]
	s_nop 1
	v_fmac_f32_dpp v48, v48, v44 row_shr:1 row_mask:0xf bank_mask:0xf
	v_fmac_f32_dpp v49, v49, v45 row_shr:1 row_mask:0xf bank_mask:0xf
	v_fmac_f32_dpp v50, v50, v46 row_shr:1 row_mask:0xf bank_mask:0xf
	v_fmac_f32_dpp v51, v51, v47 row_shr:1 row_mask:0xf bank_mask:0xf
	v_mul_f32_dpp v44, v44, v44 row_shr:1 row_mask:0xf bank_mask:0xf
	v_mul_f32_dpp v45, v45, v45 row_shr:1 row_mask:0xf bank_mask:0xf
	v_mul_f32_dpp v46, v46, v46 row_shr:1 row_mask:0xf bank_mask:0xf
	v_mul_f32_dpp v47, v47, v47 row_shr:1 row_mask:0xf bank_mask:0xf
	v_fmac_f32_dpp v48, v48, v44 row_shr:2 row_mask:0xf bank_mask:0xf
	v_fmac_f32_dpp v49, v49, v45 row_shr:2 row_mask:0xf bank_mask:0xf
	v_fmac_f32_dpp v50, v50, v46 row_shr:2 row_mask:0xf bank_mask:0xf
	v_fmac_f32_dpp v51, v51, v47 row_shr:2 row_mask:0xf bank_mask:0xf
	v_mul_f32_dpp v44, v44, v44 row_shr:2 row_mask:0xf bank_mask:0xf
	v_mul_f32_dpp v45, v45, v45 row_shr:2 row_mask:0xf bank_mask:0xf
	v_mul_f32_dpp v46, v46, v46 row_shr:2 row_mask:0xf bank_mask:0xf
	v_mul_f32_dpp v47, v47, v47 row_shr:2 row_mask:0xf bank_mask:0xf
	v_fmac_f32_dpp v48, v48, v44 row_shr:4 row_mask:0xf bank_mask:0xf
	v_fmac_f32_dpp v49, v49, v45 row_shr:4 row_mask:0xf bank_mask:0xf
	v_fmac_f32_dpp v50, v50, v46 row_shr:4 row_mask:0xf bank_mask:0xf
	v_fmac_f32_dpp v51, v51, v47 row_shr:4 row_mask:0xf bank_mask:0xf
	v_mul_f32_dpp v44, v44, v44 row_shr:4 row_mask:0xf bank_mask:0xf
	v_mul_f32_dpp v45, v45, v45 row_shr:4 row_mask:0xf bank_mask:0xf
	v_mul_f32_dpp v46, v46, v46 row_shr:4 row_mask:0xf bank_mask:0xf
	v_mul_f32_dpp v47, v47, v47 row_shr:4 row_mask:0xf bank_mask:0xf
	v_fmac_f32_dpp v48, v48, v44 row_shr:8 row_mask:0xf bank_mask:0xf
	v_fmac_f32_dpp v49, v49, v45 row_shr:8 row_mask:0xf bank_mask:0xf
	v_fmac_f32_dpp v50, v50, v46 row_shr:8 row_mask:0xf bank_mask:0xf
	v_fmac_f32_dpp v51, v51, v47 row_shr:8 row_mask:0xf bank_mask:0xf
	v_mul_f32_dpp v44, v44, v44 row_shr:8 row_mask:0xf bank_mask:0xf
	v_mul_f32_dpp v45, v45, v45 row_shr:8 row_mask:0xf bank_mask:0xf
	v_mul_f32_dpp v46, v46, v46 row_shr:8 row_mask:0xf bank_mask:0xf
	v_mul_f32_dpp v47, v47, v47 row_shr:8 row_mask:0xf bank_mask:0xf
	v_fmac_f32_dpp v48, v48, v44 row_bcast:15 row_mask:0xa bank_mask:0xf
	v_fmac_f32_dpp v49, v49, v45 row_bcast:15 row_mask:0xa bank_mask:0xf
	v_fmac_f32_dpp v50, v50, v46 row_bcast:15 row_mask:0xa bank_mask:0xf
	v_fmac_f32_dpp v51, v51, v47 row_bcast:15 row_mask:0xa bank_mask:0xf
	v_mul_f32_dpp v44, v44, v44 row_bcast:15 row_mask:0xa bank_mask:0xf
	v_mul_f32_dpp v45, v45, v45 row_bcast:15 row_mask:0xa bank_mask:0xf
	v_mul_f32_dpp v46, v46, v46 row_bcast:15 row_mask:0xa bank_mask:0xf
	v_mul_f32_dpp v47, v47, v47 row_bcast:15 row_mask:0xa bank_mask:0xf
	ds_read_b128 v[0:3], v234 offset:39136
	v_exp_f32_e32 v4, v4
	v_exp_f32_e32 v5, v5
	v_exp_f32_e32 v6, v6
	v_exp_f32_e32 v7, v7
	v_exp_f32_e32 v20, v20
	v_exp_f32_e32 v21, v21
	v_exp_f32_e32 v22, v22
	v_exp_f32_e32 v23, v23
	v_pk_add_f32 v[4:5], v[4:5], v[240:241] op_sel_hi:[1,0]
	v_pk_add_f32 v[6:7], v[6:7], v[240:241] op_sel_hi:[1,0]
	v_pk_add_f32 v[20:21], v[20:21], v[240:241] op_sel_hi:[1,0]
	v_pk_add_f32 v[22:23], v[22:23], v[240:241] op_sel_hi:[1,0]
	v_rcp_f32_e32 v4, v4
	v_rcp_f32_e32 v5, v5
	v_rcp_f32_e32 v6, v6
	v_rcp_f32_e32 v7, v7
	v_rcp_f32_e32 v20, v20
	v_rcp_f32_e32 v21, v21
	v_rcp_f32_e32 v22, v22
	v_rcp_f32_e32 v23, v23
	v_mul_f32_e32 v200, v53, v20
	v_mul_f32_e32 v201, v54, v21
	v_mul_f32_e32 v202, v58, v22
	v_mul_f32_e32 v203, v59, v23
	s_waitcnt lgkmcnt(0)
; #define LAS __attribute__((address_space(3)))
; __device__ __forceinline__ float ex2(float x) { return __builtin_amdgcn_exp2f(x); }
; __device__ __forceinline__ float rcpf_(float x) { return __builtin_amdgcn_rcpf(x); }
; __device__ __forceinline__ void lru_phase(const Ptrs& P, LAS unsigned char* lds, int G, int wave, int lane, int tid) {
;     ...
;             for (int i4 = 0; i4 < 4; ++i4) { if (mt == 2 && i4 >= 2) continue;
;                 const int s = 2 * mt + (i4 >> 1), half = i4 & 1, ch0 = 16 * s + 8 * half + 4 * hh;
;                 const f32x4 ls2 = *(const LAS f32x4*)(par + 7 * LB + ch0);
;                 float A4[4], B4[4];
; #pragma unroll
;                 for (int q = 0; q < 4; ++q) { const int i = 4 * i4 + q;
;                     const float rg = rcpf_(1.0f + ex2(gr[i])), ig = rcpf_(1.0f + ex2(gi[i]));
;                     const float la2 = ls2[q] * rg, a = ex2(la2), xx = (2.0f * LN2) * la2;
;                     const float poly = -xx * (1.0f + xx * (0.5f + xx * ((1.0f / 6.0f) + xx * ((1.0f / 24.0f) + xx * (1.0f / 120.0f)))));
;                     const float om = (xx > -0.25f) ? poly : (1.0f - a * a);
;                     A4[q] = a; B4[q] = __builtin_amdgcn_sqrtf(om) * (ig * xc[s][half][q]); }
;                 asm volatile("s_nop 1\n\t"
;                     LRU_DPP4("row_shr:1 row_mask:0xf bank_mask:0xf") LRU_DPP4("row_shr:2 row_mask:0xf bank_mask:0xf") LRU_DPP4("row_shr:4 row_mask:0xf bank_mask:0xf")
;                     LRU_DPP4("row_shr:8 row_mask:0xf bank_mask:0xf") LRU_DPP4("row_bcast:15 row_mask:0xa bank_mask:0xf")
;                     : "+v"(A4[0]), "+v"(A4[1]), "+v"(A4[2]), "+v"(A4[3]), "+v"(B4[0]), "+v"(B4[1]), "+v"(B4[2]), "+v"(B4[3]));
; #pragma unroll
;                 for (int q = 0; q < 4; ++q) { Av[s][half][q] = A4[q]; xc[s][half][q] = B4[q]; }
;                 __builtin_amdgcn_sched_barrier(0); }
	v_pk_mul_f32 v[4:5], v[4:5], v[0:1]
	v_pk_mul_f32 v[6:7], v[6:7], v[2:3]
	v_pk_mul_f32 v[204:205], v[4:5], v[242:243] op_sel_hi:[1,0]
	v_pk_mul_f32 v[206:207], v[6:7], v[242:243] op_sel_hi:[1,0]
	v_exp_f32_e32 v52, v4
	v_exp_f32_e32 v53, v5
	v_exp_f32_e32 v54, v6
	v_exp_f32_e32 v55, v7
	v_pk_fma_f32 v[208:209], v[204:205], v[244:245], v[238:239] op_sel_hi:[1,0,0]
	v_pk_fma_f32 v[210:211], v[206:207], v[244:245], v[238:239] op_sel_hi:[1,0,0]
	v_pk_fma_f32 v[208:209], v[204:205], v[208:209], v[246:247] op_sel_hi:[1,1,0]
	v_pk_fma_f32 v[210:211], v[206:207], v[210:211], v[246:247] op_sel_hi:[1,1,0]
	v_pk_fma_f32 v[208:209], v[204:205], v[208:209], v[248:249] op_sel_hi:[1,1,0]
	v_pk_fma_f32 v[210:211], v[206:207], v[210:211], v[248:249] op_sel_hi:[1,1,0]
	v_pk_fma_f32 v[208:209], v[204:205], v[208:209], v[240:241] op_sel_hi:[1,1,0]
	v_pk_fma_f32 v[210:211], v[206:207], v[210:211], v[240:241] op_sel_hi:[1,1,0]
	v_pk_mul_f32 v[208:209], v[208:209], v[204:205] neg_lo:[0,1] neg_hi:[0,1]
	v_pk_mul_f32 v[210:211], v[210:211], v[206:207] neg_lo:[0,1] neg_hi:[0,1]
	v_pk_fma_f32 v[212:213], v[52:53], v[52:53], v[240:241] op_sel_hi:[1,1,0] neg_lo:[1,0,0] neg_hi:[1,0,0]
	v_pk_fma_f32 v[214:215], v[54:55], v[54:55], v[240:241] op_sel_hi:[1,1,0] neg_lo:[1,0,0] neg_hi:[1,0,0]
	v_cmp_lt_f32_e64 s[70:71], s29, v204
	v_cmp_lt_f32_e64 s[72:73], s29, v205
	v_cmp_lt_f32_e64 s[74:75], s29, v206
	v_cmp_lt_f32_e64 s[76:77], s29, v207
	v_cndmask_b32_e64 v212, v212, v208, s[70:71]
	v_cndmask_b32_e64 v213, v213, v209, s[72:73]
	v_cndmask_b32_e64 v214, v214, v210, s[74:75]
	v_cndmask_b32_e64 v215, v215, v211, s[76:77]
	v_sqrt_f32_e32 v212, v212
	v_sqrt_f32_e32 v213, v213
	v_sqrt_f32_e32 v214, v214
	v_sqrt_f32_e32 v215, v215
	v_pk_mul_f32 v[56:57], v[200:201], v[212:213]
	v_pk_mul_f32 v[58:59], v[202:203], v[214:215]
	s_nop 1
	v_fmac_f32_dpp v56, v56, v52 row_shr:1 row_mask:0xf bank_mask:0xf
	v_fmac_f32_dpp v57, v57, v53 row_shr:1 row_mask:0xf bank_mask:0xf
	v_fmac_f32_dpp v58, v58, v54 row_shr:1 row_mask:0xf bank_mask:0xf
	v_fmac_f32_dpp v59, v59, v55 row_shr:1 row_mask:0xf bank_mask:0xf
	v_mul_f32_dpp v52, v52, v52 row_shr:1 row_mask:0xf bank_mask:0xf
	v_mul_f32_dpp v53, v53, v53 row_shr:1 row_mask:0xf bank_mask:0xf
	v_mul_f32_dpp v54, v54, v54 row_shr:1 row_mask:0xf bank_mask:0xf
	v_mul_f32_dpp v55, v55, v55 row_shr:1 row_mask:0xf bank_mask:0xf
	v_fmac_f32_dpp v56, v56, v52 row_shr:2 row_mask:0xf bank_mask:0xf
	v_fmac_f32_dpp v57, v57, v53 row_shr:2 row_mask:0xf bank_mask:0xf
	v_fmac_f32_dpp v58, v58, v54 row_shr:2 row_mask:0xf bank_mask:0xf
	v_fmac_f32_dpp v59, v59, v55 row_shr:2 row_mask:0xf bank_mask:0xf
	v_mul_f32_dpp v52, v52, v52 row_shr:2 row_mask:0xf bank_mask:0xf
	v_mul_f32_dpp v53, v53, v53 row_shr:2 row_mask:0xf bank_mask:0xf
	v_mul_f32_dpp v54, v54, v54 row_shr:2 row_mask:0xf bank_mask:0xf
	v_mul_f32_dpp v55, v55, v55 row_shr:2 row_mask:0xf bank_mask:0xf
	v_fmac_f32_dpp v56, v56, v52 row_shr:4 row_mask:0xf bank_mask:0xf
	v_fmac_f32_dpp v57, v57, v53 row_shr:4 row_mask:0xf bank_mask:0xf
	v_fmac_f32_dpp v58, v58, v54 row_shr:4 row_mask:0xf bank_mask:0xf
	v_fmac_f32_dpp v59, v59, v55 row_shr:4 row_mask:0xf bank_mask:0xf
	v_mul_f32_dpp v52, v52, v52 row_shr:4 row_mask:0xf bank_mask:0xf
	v_mul_f32_dpp v53, v53, v53 row_shr:4 row_mask:0xf bank_mask:0xf
	v_mul_f32_dpp v54, v54, v54 row_shr:4 row_mask:0xf bank_mask:0xf
	v_mul_f32_dpp v55, v55, v55 row_shr:4 row_mask:0xf bank_mask:0xf
	v_fmac_f32_dpp v56, v56, v52 row_shr:8 row_mask:0xf bank_mask:0xf
	v_fmac_f32_dpp v57, v57, v53 row_shr:8 row_mask:0xf bank_mask:0xf
	v_fmac_f32_dpp v58, v58, v54 row_shr:8 row_mask:0xf bank_mask:0xf
	v_fmac_f32_dpp v59, v59, v55 row_shr:8 row_mask:0xf bank_mask:0xf
	v_mul_f32_dpp v52, v52, v52 row_shr:8 row_mask:0xf bank_mask:0xf
	v_mul_f32_dpp v53, v53, v53 row_shr:8 row_mask:0xf bank_mask:0xf
	v_mul_f32_dpp v54, v54, v54 row_shr:8 row_mask:0xf bank_mask:0xf
	v_mul_f32_dpp v55, v55, v55 row_shr:8 row_mask:0xf bank_mask:0xf
	v_fmac_f32_dpp v56, v56, v52 row_bcast:15 row_mask:0xa bank_mask:0xf
	v_fmac_f32_dpp v57, v57, v53 row_bcast:15 row_mask:0xa bank_mask:0xf
	v_fmac_f32_dpp v58, v58, v54 row_bcast:15 row_mask:0xa bank_mask:0xf
	v_fmac_f32_dpp v59, v59, v55 row_bcast:15 row_mask:0xa bank_mask:0xf
	v_mul_f32_dpp v52, v52, v52 row_bcast:15 row_mask:0xa bank_mask:0xf
	v_mul_f32_dpp v53, v53, v53 row_bcast:15 row_mask:0xa bank_mask:0xf
	v_mul_f32_dpp v54, v54, v54 row_bcast:15 row_mask:0xa bank_mask:0xf
	v_mul_f32_dpp v55, v55, v55 row_bcast:15 row_mask:0xa bank_mask:0xf
	ds_read_b128 v[0:3], v234 offset:39168
	v_exp_f32_e32 v8, v8
	v_exp_f32_e32 v9, v9
	v_exp_f32_e32 v10, v10
	v_exp_f32_e32 v11, v11
	v_exp_f32_e32 v24, v24
	v_exp_f32_e32 v25, v25
	v_exp_f32_e32 v26, v26
	v_exp_f32_e32 v27, v27
	v_pk_add_f32 v[8:9], v[8:9], v[240:241] op_sel_hi:[1,0]
	v_pk_add_f32 v[10:11], v[10:11], v[240:241] op_sel_hi:[1,0]
	v_pk_add_f32 v[24:25], v[24:25], v[240:241] op_sel_hi:[1,0]
	v_pk_add_f32 v[26:27], v[26:27], v[240:241] op_sel_hi:[1,0]
	v_rcp_f32_e32 v8, v8
	v_rcp_f32_e32 v9, v9
	v_rcp_f32_e32 v10, v10
	v_rcp_f32_e32 v11, v11
	v_rcp_f32_e32 v24, v24
	v_rcp_f32_e32 v25, v25
	v_rcp_f32_e32 v26, v26
	v_rcp_f32_e32 v27, v27
	v_mul_f32_e32 v200, v61, v24
	v_mul_f32_e32 v201, v62, v25
	v_mul_f32_e32 v202, v66, v26
	v_mul_f32_e32 v203, v67, v27
	s_waitcnt lgkmcnt(0)
; #define LAS __attribute__((address_space(3)))
; __device__ __forceinline__ float ex2(float x) { return __builtin_amdgcn_exp2f(x); }
; __device__ __forceinline__ float rcpf_(float x) { return __builtin_amdgcn_rcpf(x); }
; __device__ __forceinline__ void lru_phase(const Ptrs& P, LAS unsigned char* lds, int G, int wave, int lane, int tid) {
;     ...
;             for (int i4 = 0; i4 < 4; ++i4) { if (mt == 2 && i4 >= 2) continue;
;                 const int s = 2 * mt + (i4 >> 1), half = i4 & 1, ch0 = 16 * s + 8 * half + 4 * hh;
;                 const f32x4 ls2 = *(const LAS f32x4*)(par + 7 * LB + ch0);
;                 float A4[4], B4[4];
; #pragma unroll
;                 for (int q = 0; q < 4; ++q) { const int i = 4 * i4 + q;
;                     const float rg = rcpf_(1.0f + ex2(gr[i])), ig = rcpf_(1.0f + ex2(gi[i]));
;                     const float la2 = ls2[q] * rg, a = ex2(la2), xx = (2.0f * LN2) * la2;
;                     const float poly = -xx * (1.0f + xx * (0.5f + xx * ((1.0f / 6.0f) + xx * ((1.0f / 24.0f) + xx * (1.0f / 120.0f)))));
;                     const float om = (xx > -0.25f) ? poly : (1.0f - a * a);
;                     A4[q] = a; B4[q] = __builtin_amdgcn_sqrtf(om) * (ig * xc[s][half][q]); }
;                 asm volatile("s_nop 1\n\t"
;                     LRU_DPP4("row_shr:1 row_mask:0xf bank_mask:0xf") LRU_DPP4("row_shr:2 row_mask:0xf bank_mask:0xf") LRU_DPP4("row_shr:4 row_mask:0xf bank_mask:0xf")
;                     LRU_DPP4("row_shr:8 row_mask:0xf bank_mask:0xf") LRU_DPP4("row_bcast:15 row_mask:0xa bank_mask:0xf")
;                     : "+v"(A4[0]), "+v"(A4[1]), "+v"(A4[2]), "+v"(A4[3]), "+v"(B4[0]), "+v"(B4[1]), "+v"(B4[2]), "+v"(B4[3]));
; #pragma unroll
;                 for (int q = 0; q < 4; ++q) { Av[s][half][q] = A4[q]; xc[s][half][q] = B4[q]; }
;                 __builtin_amdgcn_sched_barrier(0); }
	v_pk_mul_f32 v[8:9], v[8:9], v[0:1]
	v_pk_mul_f32 v[10:11], v[10:11], v[2:3]
	v_pk_mul_f32 v[204:205], v[8:9], v[242:243] op_sel_hi:[1,0]
	v_pk_mul_f32 v[206:207], v[10:11], v[242:243] op_sel_hi:[1,0]
	v_exp_f32_e32 v60, v8
	v_exp_f32_e32 v61, v9
	v_exp_f32_e32 v62, v10
	v_exp_f32_e32 v63, v11
	v_pk_fma_f32 v[208:209], v[204:205], v[244:245], v[238:239] op_sel_hi:[1,0,0]
	v_pk_fma_f32 v[210:211], v[206:207], v[244:245], v[238:239] op_sel_hi:[1,0,0]
	v_pk_fma_f32 v[208:209], v[204:205], v[208:209], v[246:247] op_sel_hi:[1,1,0]
	v_pk_fma_f32 v[210:211], v[206:207], v[210:211], v[246:247] op_sel_hi:[1,1,0]
	v_pk_fma_f32 v[208:209], v[204:205], v[208:209], v[248:249] op_sel_hi:[1,1,0]
	v_pk_fma_f32 v[210:211], v[206:207], v[210:211], v[248:249] op_sel_hi:[1,1,0]
	v_pk_fma_f32 v[208:209], v[204:205], v[208:209], v[240:241] op_sel_hi:[1,1,0]
	v_pk_fma_f32 v[210:211], v[206:207], v[210:211], v[240:241] op_sel_hi:[1,1,0]
	v_pk_mul_f32 v[208:209], v[208:209], v[204:205] neg_lo:[0,1] neg_hi:[0,1]
	v_pk_mul_f32 v[210:211], v[210:211], v[206:207] neg_lo:[0,1] neg_hi:[0,1]
	v_pk_fma_f32 v[212:213], v[60:61], v[60:61], v[240:241] op_sel_hi:[1,1,0] neg_lo:[1,0,0] neg_hi:[1,0,0]
	v_pk_fma_f32 v[214:215], v[62:63], v[62:63], v[240:241] op_sel_hi:[1,1,0] neg_lo:[1,0,0] neg_hi:[1,0,0]
	v_cmp_lt_f32_e64 s[70:71], s29, v204
	v_cmp_lt_f32_e64 s[72:73], s29, v205
	v_cmp_lt_f32_e64 s[74:75], s29, v206
	v_cmp_lt_f32_e64 s[76:77], s29, v207
	v_cndmask_b32_e64 v212, v212, v208, s[70:71]
	v_cndmask_b32_e64 v213, v213, v209, s[72:73]
	v_cndmask_b32_e64 v214, v214, v210, s[74:75]
	v_cndmask_b32_e64 v215, v215, v211, s[76:77]
	v_sqrt_f32_e32 v212, v212
	v_sqrt_f32_e32 v213, v213
	v_sqrt_f32_e32 v214, v214
	v_sqrt_f32_e32 v215, v215
	v_pk_mul_f32 v[64:65], v[200:201], v[212:213]
	v_pk_mul_f32 v[66:67], v[202:203], v[214:215]
	s_nop 1
	v_fmac_f32_dpp v64, v64, v60 row_shr:1 row_mask:0xf bank_mask:0xf
	v_fmac_f32_dpp v65, v65, v61 row_shr:1 row_mask:0xf bank_mask:0xf
	v_fmac_f32_dpp v66, v66, v62 row_shr:1 row_mask:0xf bank_mask:0xf
	v_fmac_f32_dpp v67, v67, v63 row_shr:1 row_mask:0xf bank_mask:0xf
	v_mul_f32_dpp v60, v60, v60 row_shr:1 row_mask:0xf bank_mask:0xf
	v_mul_f32_dpp v61, v61, v61 row_shr:1 row_mask:0xf bank_mask:0xf
	v_mul_f32_dpp v62, v62, v62 row_shr:1 row_mask:0xf bank_mask:0xf
	v_mul_f32_dpp v63, v63, v63 row_shr:1 row_mask:0xf bank_mask:0xf
	v_fmac_f32_dpp v64, v64, v60 row_shr:2 row_mask:0xf bank_mask:0xf
	v_fmac_f32_dpp v65, v65, v61 row_shr:2 row_mask:0xf bank_mask:0xf
	v_fmac_f32_dpp v66, v66, v62 row_shr:2 row_mask:0xf bank_mask:0xf
	v_fmac_f32_dpp v67, v67, v63 row_shr:2 row_mask:0xf bank_mask:0xf
	v_mul_f32_dpp v60, v60, v60 row_shr:2 row_mask:0xf bank_mask:0xf
	v_mul_f32_dpp v61, v61, v61 row_shr:2 row_mask:0xf bank_mask:0xf
	v_mul_f32_dpp v62, v62, v62 row_shr:2 row_mask:0xf bank_mask:0xf
	v_mul_f32_dpp v63, v63, v63 row_shr:2 row_mask:0xf bank_mask:0xf
	v_fmac_f32_dpp v64, v64, v60 row_shr:4 row_mask:0xf bank_mask:0xf
	v_fmac_f32_dpp v65, v65, v61 row_shr:4 row_mask:0xf bank_mask:0xf
	v_fmac_f32_dpp v66, v66, v62 row_shr:4 row_mask:0xf bank_mask:0xf
	v_fmac_f32_dpp v67, v67, v63 row_shr:4 row_mask:0xf bank_mask:0xf
	v_mul_f32_dpp v60, v60, v60 row_shr:4 row_mask:0xf bank_mask:0xf
	v_mul_f32_dpp v61, v61, v61 row_shr:4 row_mask:0xf bank_mask:0xf
	v_mul_f32_dpp v62, v62, v62 row_shr:4 row_mask:0xf bank_mask:0xf
	v_mul_f32_dpp v63, v63, v63 row_shr:4 row_mask:0xf bank_mask:0xf
	v_fmac_f32_dpp v64, v64, v60 row_shr:8 row_mask:0xf bank_mask:0xf
	v_fmac_f32_dpp v65, v65, v61 row_shr:8 row_mask:0xf bank_mask:0xf
	v_fmac_f32_dpp v66, v66, v62 row_shr:8 row_mask:0xf bank_mask:0xf
	v_fmac_f32_dpp v67, v67, v63 row_shr:8 row_mask:0xf bank_mask:0xf
	v_mul_f32_dpp v60, v60, v60 row_shr:8 row_mask:0xf bank_mask:0xf
	v_mul_f32_dpp v61, v61, v61 row_shr:8 row_mask:0xf bank_mask:0xf
	v_mul_f32_dpp v62, v62, v62 row_shr:8 row_mask:0xf bank_mask:0xf
	v_mul_f32_dpp v63, v63, v63 row_shr:8 row_mask:0xf bank_mask:0xf
	v_fmac_f32_dpp v64, v64, v60 row_bcast:15 row_mask:0xa bank_mask:0xf
	v_fmac_f32_dpp v65, v65, v61 row_bcast:15 row_mask:0xa bank_mask:0xf
	v_fmac_f32_dpp v66, v66, v62 row_bcast:15 row_mask:0xa bank_mask:0xf
	v_fmac_f32_dpp v67, v67, v63 row_bcast:15 row_mask:0xa bank_mask:0xf
	v_mul_f32_dpp v60, v60, v60 row_bcast:15 row_mask:0xa bank_mask:0xf
	v_mul_f32_dpp v61, v61, v61 row_bcast:15 row_mask:0xa bank_mask:0xf
	v_mul_f32_dpp v62, v62, v62 row_bcast:15 row_mask:0xa bank_mask:0xf
	v_mul_f32_dpp v63, v63, v63 row_bcast:15 row_mask:0xa bank_mask:0xf
	ds_read_b128 v[0:3], v234 offset:39200
	v_exp_f32_e32 v12, v12
	v_exp_f32_e32 v13, v13
	v_exp_f32_e32 v14, v14
	v_exp_f32_e32 v15, v15
	v_exp_f32_e32 v28, v28
	v_exp_f32_e32 v29, v29
	v_exp_f32_e32 v30, v30
	v_exp_f32_e32 v31, v31
	v_pk_add_f32 v[12:13], v[12:13], v[240:241] op_sel_hi:[1,0]
	v_pk_add_f32 v[14:15], v[14:15], v[240:241] op_sel_hi:[1,0]
	v_pk_add_f32 v[28:29], v[28:29], v[240:241] op_sel_hi:[1,0]
	v_pk_add_f32 v[30:31], v[30:31], v[240:241] op_sel_hi:[1,0]
	v_rcp_f32_e32 v12, v12
	v_rcp_f32_e32 v13, v13
	v_rcp_f32_e32 v14, v14
	v_rcp_f32_e32 v15, v15
	v_rcp_f32_e32 v28, v28
	v_rcp_f32_e32 v29, v29
	v_rcp_f32_e32 v30, v30
	v_rcp_f32_e32 v31, v31
	v_mul_f32_e32 v200, v69, v28
	v_mul_f32_e32 v201, v70, v29
	v_mul_f32_e32 v202, v74, v30
	v_mul_f32_e32 v203, v75, v31
	s_waitcnt lgkmcnt(0)
; #define LAS __attribute__((address_space(3)))
; __device__ __forceinline__ float ex2(float x) { return __builtin_amdgcn_exp2f(x); }
; __device__ __forceinline__ float rcpf_(float x) { return __builtin_amdgcn_rcpf(x); }
; __device__ __forceinline__ void lru_phase(const Ptrs& P, LAS unsigned char* lds, int G, int wave, int lane, int tid) {
;     ...
;             for (int i4 = 0; i4 < 4; ++i4) { if (mt == 2 && i4 >= 2) continue;
;                 const int s = 2 * mt + (i4 >> 1), half = i4 & 1, ch0 = 16 * s + 8 * half + 4 * hh;
;                 const f32x4 ls2 = *(const LAS f32x4*)(par + 7 * LB + ch0);
;                 float A4[4], B4[4];
; #pragma unroll
;                 for (int q = 0; q < 4; ++q) { const int i = 4 * i4 + q;
;                     const float rg = rcpf_(1.0f + ex2(gr[i])), ig = rcpf_(1.0f + ex2(gi[i]));
;                     const float la2 = ls2[q] * rg, a = ex2(la2), xx = (2.0f * LN2) * la2;
;                     const float poly = -xx * (1.0f + xx * (0.5f + xx * ((1.0f / 6.0f) + xx * ((1.0f / 24.0f) + xx * (1.0f / 120.0f)))));
;                     const float om = (xx > -0.25f) ? poly : (1.0f - a * a);
;                     A4[q] = a; B4[q] = __builtin_amdgcn_sqrtf(om) * (ig * xc[s][half][q]); }
;                 asm volatile("s_nop 1\n\t"
;                     LRU_DPP4("row_shr:1 row_mask:0xf bank_mask:0xf") LRU_DPP4("row_shr:2 row_mask:0xf bank_mask:0xf") LRU_DPP4("row_shr:4 row_mask:0xf bank_mask:0xf")
;                     LRU_DPP4("row_shr:8 row_mask:0xf bank_mask:0xf") LRU_DPP4("row_bcast:15 row_mask:0xa bank_mask:0xf")
;                     : "+v"(A4[0]), "+v"(A4[1]), "+v"(A4[2]), "+v"(A4[3]), "+v"(B4[0]), "+v"(B4[1]), "+v"(B4[2]), "+v"(B4[3]));
; #pragma unroll
;                 for (int q = 0; q < 4; ++q) { Av[s][half][q] = A4[q]; xc[s][half][q] = B4[q]; }
;                 __builtin_amdgcn_sched_barrier(0); }
	v_pk_mul_f32 v[12:13], v[12:13], v[0:1]
	v_pk_mul_f32 v[14:15], v[14:15], v[2:3]
	v_pk_mul_f32 v[204:205], v[12:13], v[242:243] op_sel_hi:[1,0]
	v_pk_mul_f32 v[206:207], v[14:15], v[242:243] op_sel_hi:[1,0]
	v_exp_f32_e32 v68, v12
	v_exp_f32_e32 v69, v13
	v_exp_f32_e32 v70, v14
	v_exp_f32_e32 v71, v15
	v_pk_fma_f32 v[208:209], v[204:205], v[244:245], v[238:239] op_sel_hi:[1,0,0]
	v_pk_fma_f32 v[210:211], v[206:207], v[244:245], v[238:239] op_sel_hi:[1,0,0]
	v_pk_fma_f32 v[208:209], v[204:205], v[208:209], v[246:247] op_sel_hi:[1,1,0]
	v_pk_fma_f32 v[210:211], v[206:207], v[210:211], v[246:247] op_sel_hi:[1,1,0]
	v_pk_fma_f32 v[208:209], v[204:205], v[208:209], v[248:249] op_sel_hi:[1,1,0]
	v_pk_fma_f32 v[210:211], v[206:207], v[210:211], v[248:249] op_sel_hi:[1,1,0]
	v_pk_fma_f32 v[208:209], v[204:205], v[208:209], v[240:241] op_sel_hi:[1,1,0]
	v_pk_fma_f32 v[210:211], v[206:207], v[210:211], v[240:241] op_sel_hi:[1,1,0]
	v_pk_mul_f32 v[208:209], v[208:209], v[204:205] neg_lo:[0,1] neg_hi:[0,1]
	v_pk_mul_f32 v[210:211], v[210:211], v[206:207] neg_lo:[0,1] neg_hi:[0,1]
	v_pk_fma_f32 v[212:213], v[68:69], v[68:69], v[240:241] op_sel_hi:[1,1,0] neg_lo:[1,0,0] neg_hi:[1,0,0]
	v_pk_fma_f32 v[214:215], v[70:71], v[70:71], v[240:241] op_sel_hi:[1,1,0] neg_lo:[1,0,0] neg_hi:[1,0,0]
	v_cmp_lt_f32_e64 s[70:71], s29, v204
	v_cmp_lt_f32_e64 s[72:73], s29, v205
	v_cmp_lt_f32_e64 s[74:75], s29, v206
	v_cmp_lt_f32_e64 s[76:77], s29, v207
	v_cndmask_b32_e64 v212, v212, v208, s[70:71]
	v_cndmask_b32_e64 v213, v213, v209, s[72:73]
	v_cndmask_b32_e64 v214, v214, v210, s[74:75]
	v_cndmask_b32_e64 v215, v215, v211, s[76:77]
	v_sqrt_f32_e32 v212, v212
	v_sqrt_f32_e32 v213, v213
	v_sqrt_f32_e32 v214, v214
	v_sqrt_f32_e32 v215, v215
	v_pk_mul_f32 v[72:73], v[200:201], v[212:213]
	v_pk_mul_f32 v[74:75], v[202:203], v[214:215]
	s_nop 1
	v_fmac_f32_dpp v72, v72, v68 row_shr:1 row_mask:0xf bank_mask:0xf
	v_fmac_f32_dpp v73, v73, v69 row_shr:1 row_mask:0xf bank_mask:0xf
	v_fmac_f32_dpp v74, v74, v70 row_shr:1 row_mask:0xf bank_mask:0xf
	v_fmac_f32_dpp v75, v75, v71 row_shr:1 row_mask:0xf bank_mask:0xf
	v_mul_f32_dpp v68, v68, v68 row_shr:1 row_mask:0xf bank_mask:0xf
	v_mul_f32_dpp v69, v69, v69 row_shr:1 row_mask:0xf bank_mask:0xf
	v_mul_f32_dpp v70, v70, v70 row_shr:1 row_mask:0xf bank_mask:0xf
	v_mul_f32_dpp v71, v71, v71 row_shr:1 row_mask:0xf bank_mask:0xf
	v_fmac_f32_dpp v72, v72, v68 row_shr:2 row_mask:0xf bank_mask:0xf
	v_fmac_f32_dpp v73, v73, v69 row_shr:2 row_mask:0xf bank_mask:0xf
	v_fmac_f32_dpp v74, v74, v70 row_shr:2 row_mask:0xf bank_mask:0xf
	v_fmac_f32_dpp v75, v75, v71 row_shr:2 row_mask:0xf bank_mask:0xf
	v_mul_f32_dpp v68, v68, v68 row_shr:2 row_mask:0xf bank_mask:0xf
	v_mul_f32_dpp v69, v69, v69 row_shr:2 row_mask:0xf bank_mask:0xf
	v_mul_f32_dpp v70, v70, v70 row_shr:2 row_mask:0xf bank_mask:0xf
	v_mul_f32_dpp v71, v71, v71 row_shr:2 row_mask:0xf bank_mask:0xf
	v_fmac_f32_dpp v72, v72, v68 row_shr:4 row_mask:0xf bank_mask:0xf
	v_fmac_f32_dpp v73, v73, v69 row_shr:4 row_mask:0xf bank_mask:0xf
	v_fmac_f32_dpp v74, v74, v70 row_shr:4 row_mask:0xf bank_mask:0xf
	v_fmac_f32_dpp v75, v75, v71 row_shr:4 row_mask:0xf bank_mask:0xf
	v_mul_f32_dpp v68, v68, v68 row_shr:4 row_mask:0xf bank_mask:0xf
	v_mul_f32_dpp v69, v69, v69 row_shr:4 row_mask:0xf bank_mask:0xf
	v_mul_f32_dpp v70, v70, v70 row_shr:4 row_mask:0xf bank_mask:0xf
	v_mul_f32_dpp v71, v71, v71 row_shr:4 row_mask:0xf bank_mask:0xf
	v_fmac_f32_dpp v72, v72, v68 row_shr:8 row_mask:0xf bank_mask:0xf
	v_fmac_f32_dpp v73, v73, v69 row_shr:8 row_mask:0xf bank_mask:0xf
	v_fmac_f32_dpp v74, v74, v70 row_shr:8 row_mask:0xf bank_mask:0xf
	v_fmac_f32_dpp v75, v75, v71 row_shr:8 row_mask:0xf bank_mask:0xf
	v_mul_f32_dpp v68, v68, v68 row_shr:8 row_mask:0xf bank_mask:0xf
	v_mul_f32_dpp v69, v69, v69 row_shr:8 row_mask:0xf bank_mask:0xf
	v_mul_f32_dpp v70, v70, v70 row_shr:8 row_mask:0xf bank_mask:0xf
	v_mul_f32_dpp v71, v71, v71 row_shr:8 row_mask:0xf bank_mask:0xf
	v_fmac_f32_dpp v72, v72, v68 row_bcast:15 row_mask:0xa bank_mask:0xf
	v_fmac_f32_dpp v73, v73, v69 row_bcast:15 row_mask:0xa bank_mask:0xf
	v_fmac_f32_dpp v74, v74, v70 row_bcast:15 row_mask:0xa bank_mask:0xf
	v_fmac_f32_dpp v75, v75, v71 row_bcast:15 row_mask:0xa bank_mask:0xf
	v_mul_f32_dpp v68, v68, v68 row_bcast:15 row_mask:0xa bank_mask:0xf
	v_mul_f32_dpp v69, v69, v69 row_bcast:15 row_mask:0xa bank_mask:0xf
	v_mul_f32_dpp v70, v70, v70 row_bcast:15 row_mask:0xa bank_mask:0xf
	v_mul_f32_dpp v71, v71, v71 row_bcast:15 row_mask:0xa bank_mask:0xf

; #define LAS __attribute__((address_space(3)))
; __device__ __forceinline__ void lru_phase(const Ptrs& P, LAS unsigned char* lds, int G, int wave, int lane, int tid) {
;     ...
;         for (int mt = 0; mt < 3; ++mt) {
;             f32x16 gr, gi;
; #pragma unroll
;             for (int i = 0; i < 16; ++i) { gr[i] = 0.f; gi[i] = 0.f; }
;             const LAS bf16x8* wa = (const LAS bf16x8*)(lds + L_WGF) + (size_t)(mt * 6) * 64 + lane;
;             const LAS bf16x8* wb = (const LAS bf16x8*)(lds + L_WGF) + (size_t)((3 + mt) * 6) * 64 + lane;
; #pragma unroll
;             for (int s = 0; s < 5; ++s) { gr = MFMA32(wa[s * 64], xf[s], gr); gi = MFMA32(wb[s * 64], xf[s], gi); }
;             gr = MFMA32(wa[5 * 64], xone, gr); gi = MFMA32(wb[5 * 64], xone, gi);
;             __builtin_amdgcn_sched_barrier(0);
; #pragma unroll
;             for (int i4 = 0; i4 < 4; ++i4) { if (mt == 2 && i4 >= 2) continue;
;                 const int s = 2 * mt + (i4 >> 1), half = i4 & 1, ch0 = 16 * s + 8 * half + 4 * hh;
;                 const f32x4 ls2 = *(const LAS f32x4*)(par + 7 * LB + ch0);
;                 float A4[4], B4[4];
; #pragma unroll
;                 for (int q = 0; q < 4; ++q) { const int i = 4 * i4 + q;
;                     const float rg = rcpf_(1.0f + ex2(gr[i])), ig = rcpf_(1.0f + ex2(gi[i]));
;                     const float la2 = ls2[q] * rg, a = ex2(la2), xx = (2.0f * LN2) * la2;
;                     const float poly = -xx * (1.0f + xx * (0.5f + xx * ((1.0f / 6.0f) + xx * ((1.0f / 24.0f) + xx * (1.0f / 120.0f)))));
;                     const float om = (xx > -0.25f) ? poly : (1.0f - a * a);
;                     A4[q] = a; B4[q] = __builtin_amdgcn_sqrtf(om) * (ig * xc[s][half][q]); }
;                 asm volatile("s_nop 1\n\t"
;                     LRU_DPP4("row_shr:1 row_mask:0xf bank_mask:0xf") LRU_DPP4("row_shr:2 row_mask:0xf bank_mask:0xf") LRU_DPP4("row_shr:4 row_mask:0xf bank_mask:0xf")
;                     LRU_DPP4("row_shr:8 row_mask:0xf bank_mask:0xf") LRU_DPP4("row_bcast:15 row_mask:0xa bank_mask:0xf")
;                     : "+v"(A4[0]), "+v"(A4[1]), "+v"(A4[2]), "+v"(A4[3]), "+v"(B4[0]), "+v"(B4[1]), "+v"(B4[2]), "+v"(B4[3]));
; #pragma unroll
;                 for (int q = 0; q < 4; ++q) { Av[s][half][q] = A4[q]; xc[s][half][q] = B4[q]; }
;                 __builtin_amdgcn_sched_barrier(0); }
	ds_read_b128 v[0:3], v237 offset:6144
	ds_read_b128 v[140:143], v237 offset:7168
	ds_read_b128 v[16:19], v237 offset:24576
	ds_read_b128 v[144:147], v237 offset:25600
	s_waitcnt lgkmcnt(3)
	v_mfma_f32_32x32x16_bf16 v[0:15], v[0:3], v[36:39], 0
	s_waitcnt lgkmcnt(1)
	v_mfma_f32_32x32x16_bf16 v[16:31], v[16:19], v[36:39], 0
	v_mfma_f32_32x32x16_bf16 v[0:15], v[140:143], v[40:43], v[0:15]
	s_waitcnt lgkmcnt(0)
	v_mfma_f32_32x32x16_bf16 v[16:31], v[144:147], v[40:43], v[16:31]
	ds_read_b128 v[140:143], v237 offset:8192
	ds_read_b128 v[144:147], v237 offset:9216
	s_waitcnt lgkmcnt(1)
	v_mfma_f32_32x32x16_bf16 v[0:15], v[140:143], v[76:79], v[0:15]
	ds_read_b128 v[140:143], v237 offset:26624
	ds_read_b128 v[148:151], v237 offset:27648
	s_waitcnt lgkmcnt(1)
	v_mfma_f32_32x32x16_bf16 v[16:31], v[140:143], v[76:79], v[16:31]
	v_mfma_f32_32x32x16_bf16 v[0:15], v[144:147], v[112:115], v[0:15]
	ds_read_b128 v[140:143], v237 offset:10240
	ds_read_b128 v[144:147], v237 offset:11264
	s_waitcnt lgkmcnt(2)
	v_mfma_f32_32x32x16_bf16 v[16:31], v[148:151], v[112:115], v[16:31]
	s_waitcnt lgkmcnt(1)
	v_mfma_f32_32x32x16_bf16 v[0:15], v[140:143], v[124:127], v[0:15]
	ds_read_b128 v[140:143], v237 offset:28672
	ds_read_b128 v[148:151], v237 offset:29696
	s_waitcnt lgkmcnt(1)
	v_mfma_f32_32x32x16_bf16 v[16:31], v[140:143], v[124:127], v[16:31]
	v_mfma_f32_32x32x16_bf16 v[0:15], v[144:147], v[32:35], v[0:15]
	s_waitcnt lgkmcnt(0)
	v_mfma_f32_32x32x16_bf16 v[16:31], v[148:151], v[32:35], v[16:31]
	s_nop 9
	ds_read_b128 v[140:143], v234 offset:39232
	v_exp_f32_e32 v0, v0
	v_exp_f32_e32 v1, v1
	v_exp_f32_e32 v2, v2
	v_exp_f32_e32 v3, v3
	v_exp_f32_e32 v16, v16
	v_exp_f32_e32 v17, v17
	v_exp_f32_e32 v18, v18
	v_exp_f32_e32 v19, v19
	v_pk_add_f32 v[0:1], v[0:1], v[240:241] op_sel_hi:[1,0]
	v_pk_add_f32 v[2:3], v[2:3], v[240:241] op_sel_hi:[1,0]
	v_pk_add_f32 v[16:17], v[16:17], v[240:241] op_sel_hi:[1,0]
	v_pk_add_f32 v[18:19], v[18:19], v[240:241] op_sel_hi:[1,0]
	v_rcp_f32_e32 v0, v0
	v_rcp_f32_e32 v1, v1
	v_rcp_f32_e32 v2, v2
	v_rcp_f32_e32 v3, v3
	v_rcp_f32_e32 v16, v16
	v_rcp_f32_e32 v17, v17
	v_rcp_f32_e32 v18, v18
	v_rcp_f32_e32 v19, v19
	v_mul_f32_e32 v200, v81, v16
	v_mul_f32_e32 v201, v82, v17
	v_mul_f32_e32 v202, v86, v18
	v_mul_f32_e32 v203, v87, v19
	s_waitcnt lgkmcnt(0)
	v_pk_mul_f32 v[0:1], v[0:1], v[140:141]
	v_pk_mul_f32 v[2:3], v[2:3], v[142:143]
	v_pk_mul_f32 v[204:205], v[0:1], v[242:243] op_sel_hi:[1,0]
	v_pk_mul_f32 v[206:207], v[2:3], v[242:243] op_sel_hi:[1,0]
	v_exp_f32_e32 v80, v0
	v_exp_f32_e32 v81, v1
	v_exp_f32_e32 v82, v2
	v_exp_f32_e32 v83, v3
	v_pk_fma_f32 v[208:209], v[204:205], v[244:245], v[238:239] op_sel_hi:[1,0,0]
	v_pk_fma_f32 v[210:211], v[206:207], v[244:245], v[238:239] op_sel_hi:[1,0,0]
	v_pk_fma_f32 v[208:209], v[204:205], v[208:209], v[246:247] op_sel_hi:[1,1,0]
	v_pk_fma_f32 v[210:211], v[206:207], v[210:211], v[246:247] op_sel_hi:[1,1,0]
	v_pk_fma_f32 v[208:209], v[204:205], v[208:209], v[248:249] op_sel_hi:[1,1,0]
	v_pk_fma_f32 v[210:211], v[206:207], v[210:211], v[248:249] op_sel_hi:[1,1,0]
	v_pk_fma_f32 v[208:209], v[204:205], v[208:209], v[240:241] op_sel_hi:[1,1,0]
	v_pk_fma_f32 v[210:211], v[206:207], v[210:211], v[240:241] op_sel_hi:[1,1,0]
	v_pk_mul_f32 v[208:209], v[208:209], v[204:205] neg_lo:[0,1] neg_hi:[0,1]
	v_pk_mul_f32 v[210:211], v[210:211], v[206:207] neg_lo:[0,1] neg_hi:[0,1]
	v_pk_fma_f32 v[212:213], v[80:81], v[80:81], v[240:241] op_sel_hi:[1,1,0] neg_lo:[1,0,0] neg_hi:[1,0,0]
	v_pk_fma_f32 v[214:215], v[82:83], v[82:83], v[240:241] op_sel_hi:[1,1,0] neg_lo:[1,0,0] neg_hi:[1,0,0]
	v_cmp_lt_f32_e64 s[70:71], s29, v204
	v_cmp_lt_f32_e64 s[72:73], s29, v205
	v_cmp_lt_f32_e64 s[74:75], s29, v206
	v_cmp_lt_f32_e64 s[76:77], s29, v207
	v_cndmask_b32_e64 v212, v212, v208, s[70:71]
	v_cndmask_b32_e64 v213, v213, v209, s[72:73]
	v_cndmask_b32_e64 v214, v214, v210, s[74:75]
	v_cndmask_b32_e64 v215, v215, v211, s[76:77]
	v_sqrt_f32_e32 v212, v212
	v_sqrt_f32_e32 v213, v213
	v_sqrt_f32_e32 v214, v214
	v_sqrt_f32_e32 v215, v215
	v_pk_mul_f32 v[84:85], v[200:201], v[212:213]
	v_pk_mul_f32 v[86:87], v[202:203], v[214:215]
	s_nop 1
	v_fmac_f32_dpp v84, v84, v80 row_shr:1 row_mask:0xf bank_mask:0xf
	v_fmac_f32_dpp v85, v85, v81 row_shr:1 row_mask:0xf bank_mask:0xf
	v_fmac_f32_dpp v86, v86, v82 row_shr:1 row_mask:0xf bank_mask:0xf
	v_fmac_f32_dpp v87, v87, v83 row_shr:1 row_mask:0xf bank_mask:0xf
	v_mul_f32_dpp v80, v80, v80 row_shr:1 row_mask:0xf bank_mask:0xf
	v_mul_f32_dpp v81, v81, v81 row_shr:1 row_mask:0xf bank_mask:0xf
	v_mul_f32_dpp v82, v82, v82 row_shr:1 row_mask:0xf bank_mask:0xf
	v_mul_f32_dpp v83, v83, v83 row_shr:1 row_mask:0xf bank_mask:0xf
	v_fmac_f32_dpp v84, v84, v80 row_shr:2 row_mask:0xf bank_mask:0xf
	v_fmac_f32_dpp v85, v85, v81 row_shr:2 row_mask:0xf bank_mask:0xf
	v_fmac_f32_dpp v86, v86, v82 row_shr:2 row_mask:0xf bank_mask:0xf
	v_fmac_f32_dpp v87, v87, v83 row_shr:2 row_mask:0xf bank_mask:0xf
	v_mul_f32_dpp v80, v80, v80 row_shr:2 row_mask:0xf bank_mask:0xf
	v_mul_f32_dpp v81, v81, v81 row_shr:2 row_mask:0xf bank_mask:0xf
	v_mul_f32_dpp v82, v82, v82 row_shr:2 row_mask:0xf bank_mask:0xf
	v_mul_f32_dpp v83, v83, v83 row_shr:2 row_mask:0xf bank_mask:0xf
	v_fmac_f32_dpp v84, v84, v80 row_shr:4 row_mask:0xf bank_mask:0xf
	v_fmac_f32_dpp v85, v85, v81 row_shr:4 row_mask:0xf bank_mask:0xf
	v_fmac_f32_dpp v86, v86, v82 row_shr:4 row_mask:0xf bank_mask:0xf
	v_fmac_f32_dpp v87, v87, v83 row_shr:4 row_mask:0xf bank_mask:0xf
	v_mul_f32_dpp v80, v80, v80 row_shr:4 row_mask:0xf bank_mask:0xf
	v_mul_f32_dpp v81, v81, v81 row_shr:4 row_mask:0xf bank_mask:0xf
	v_mul_f32_dpp v82, v82, v82 row_shr:4 row_mask:0xf bank_mask:0xf
; #define LAS __attribute__((address_space(3)))
; __device__ __forceinline__ float ex2(float x) { return __builtin_amdgcn_exp2f(x); }
; __device__ __forceinline__ float rcpf_(float x) { return __builtin_amdgcn_rcpf(x); }
; __device__ __forceinline__ void lru_phase(const Ptrs& P, LAS unsigned char* lds, int G, int wave, int lane, int tid) {
;     ...
; #pragma unroll
;             for (int i4 = 0; i4 < 4; ++i4) { if (mt == 2 && i4 >= 2) continue;
;                 const int s = 2 * mt + (i4 >> 1), half = i4 & 1, ch0 = 16 * s + 8 * half + 4 * hh;
;                 const f32x4 ls2 = *(const LAS f32x4*)(par + 7 * LB + ch0);
;                 float A4[4], B4[4];
; #pragma unroll
;                 for (int q = 0; q < 4; ++q) { const int i = 4 * i4 + q;
;                     const float rg = rcpf_(1.0f + ex2(gr[i])), ig = rcpf_(1.0f + ex2(gi[i]));
;                     const float la2 = ls2[q] * rg, a = ex2(la2), xx = (2.0f * LN2) * la2;
;                     const float poly = -xx * (1.0f + xx * (0.5f + xx * ((1.0f / 6.0f) + xx * ((1.0f / 24.0f) + xx * (1.0f / 120.0f)))));
;                     const float om = (xx > -0.25f) ? poly : (1.0f - a * a);
;                     A4[q] = a; B4[q] = __builtin_amdgcn_sqrtf(om) * (ig * xc[s][half][q]); }
;                 asm volatile("s_nop 1\n\t"
;                     LRU_DPP4("row_shr:1 row_mask:0xf bank_mask:0xf") LRU_DPP4("row_shr:2 row_mask:0xf bank_mask:0xf") LRU_DPP4("row_shr:4 row_mask:0xf bank_mask:0xf")
;                     LRU_DPP4("row_shr:8 row_mask:0xf bank_mask:0xf") LRU_DPP4("row_bcast:15 row_mask:0xa bank_mask:0xf")
;                     : "+v"(A4[0]), "+v"(A4[1]), "+v"(A4[2]), "+v"(A4[3]), "+v"(B4[0]), "+v"(B4[1]), "+v"(B4[2]), "+v"(B4[3]));
; #pragma unroll
;                 for (int q = 0; q < 4; ++q) { Av[s][half][q] = A4[q]; xc[s][half][q] = B4[q]; }
;                 __builtin_amdgcn_sched_barrier(0); }
	v_mul_f32_dpp v83, v83, v83 row_shr:4 row_mask:0xf bank_mask:0xf
	v_fmac_f32_dpp v84, v84, v80 row_shr:8 row_mask:0xf bank_mask:0xf
	v_fmac_f32_dpp v85, v85, v81 row_shr:8 row_mask:0xf bank_mask:0xf
	v_fmac_f32_dpp v86, v86, v82 row_shr:8 row_mask:0xf bank_mask:0xf
	v_fmac_f32_dpp v87, v87, v83 row_shr:8 row_mask:0xf bank_mask:0xf
	v_mul_f32_dpp v80, v80, v80 row_shr:8 row_mask:0xf bank_mask:0xf
	v_mul_f32_dpp v81, v81, v81 row_shr:8 row_mask:0xf bank_mask:0xf
	v_mul_f32_dpp v82, v82, v82 row_shr:8 row_mask:0xf bank_mask:0xf
	v_mul_f32_dpp v83, v83, v83 row_shr:8 row_mask:0xf bank_mask:0xf
	v_fmac_f32_dpp v84, v84, v80 row_bcast:15 row_mask:0xa bank_mask:0xf
	v_fmac_f32_dpp v85, v85, v81 row_bcast:15 row_mask:0xa bank_mask:0xf
	v_fmac_f32_dpp v86, v86, v82 row_bcast:15 row_mask:0xa bank_mask:0xf
	v_fmac_f32_dpp v87, v87, v83 row_bcast:15 row_mask:0xa bank_mask:0xf
	v_mul_f32_dpp v80, v80, v80 row_bcast:15 row_mask:0xa bank_mask:0xf
	v_mul_f32_dpp v81, v81, v81 row_bcast:15 row_mask:0xa bank_mask:0xf
	v_mul_f32_dpp v82, v82, v82 row_bcast:15 row_mask:0xa bank_mask:0xf
	v_mul_f32_dpp v83, v83, v83 row_bcast:15 row_mask:0xa bank_mask:0xf
	ds_read_b128 v[0:3], v234 offset:39264
	v_exp_f32_e32 v4, v4
	v_exp_f32_e32 v5, v5
	v_exp_f32_e32 v6, v6
	v_exp_f32_e32 v7, v7
	v_exp_f32_e32 v20, v20
	v_exp_f32_e32 v21, v21
	v_exp_f32_e32 v22, v22
	v_exp_f32_e32 v23, v23
	v_pk_add_f32 v[4:5], v[4:5], v[240:241] op_sel_hi:[1,0]
	v_pk_add_f32 v[6:7], v[6:7], v[240:241] op_sel_hi:[1,0]
	v_pk_add_f32 v[20:21], v[20:21], v[240:241] op_sel_hi:[1,0]
	v_pk_add_f32 v[22:23], v[22:23], v[240:241] op_sel_hi:[1,0]
	v_rcp_f32_e32 v4, v4
	v_rcp_f32_e32 v5, v5
	v_rcp_f32_e32 v6, v6
	v_rcp_f32_e32 v7, v7
	v_rcp_f32_e32 v20, v20
	v_rcp_f32_e32 v21, v21
	v_rcp_f32_e32 v22, v22
	v_rcp_f32_e32 v23, v23
	v_mul_f32_e32 v200, v89, v20
	v_mul_f32_e32 v201, v90, v21
	v_mul_f32_e32 v202, v94, v22
	v_mul_f32_e32 v203, v95, v23
	s_waitcnt lgkmcnt(0)
	v_pk_mul_f32 v[4:5], v[4:5], v[0:1]
	v_pk_mul_f32 v[6:7], v[6:7], v[2:3]
	v_pk_mul_f32 v[204:205], v[4:5], v[242:243] op_sel_hi:[1,0]
	v_pk_mul_f32 v[206:207], v[6:7], v[242:243] op_sel_hi:[1,0]
	v_exp_f32_e32 v88, v4
	v_exp_f32_e32 v89, v5
	v_exp_f32_e32 v90, v6
	v_exp_f32_e32 v91, v7
	v_pk_fma_f32 v[208:209], v[204:205], v[244:245], v[238:239] op_sel_hi:[1,0,0]
	v_pk_fma_f32 v[210:211], v[206:207], v[244:245], v[238:239] op_sel_hi:[1,0,0]
	v_pk_fma_f32 v[208:209], v[204:205], v[208:209], v[246:247] op_sel_hi:[1,1,0]
	v_pk_fma_f32 v[210:211], v[206:207], v[210:211], v[246:247] op_sel_hi:[1,1,0]
	v_pk_fma_f32 v[208:209], v[204:205], v[208:209], v[248:249] op_sel_hi:[1,1,0]
	v_pk_fma_f32 v[210:211], v[206:207], v[210:211], v[248:249] op_sel_hi:[1,1,0]
	v_pk_fma_f32 v[208:209], v[204:205], v[208:209], v[240:241] op_sel_hi:[1,1,0]
	v_pk_fma_f32 v[210:211], v[206:207], v[210:211], v[240:241] op_sel_hi:[1,1,0]
	v_pk_mul_f32 v[208:209], v[208:209], v[204:205] neg_lo:[0,1] neg_hi:[0,1]
	v_pk_mul_f32 v[210:211], v[210:211], v[206:207] neg_lo:[0,1] neg_hi:[0,1]
	v_pk_fma_f32 v[212:213], v[88:89], v[88:89], v[240:241] op_sel_hi:[1,1,0] neg_lo:[1,0,0] neg_hi:[1,0,0]
	v_pk_fma_f32 v[214:215], v[90:91], v[90:91], v[240:241] op_sel_hi:[1,1,0] neg_lo:[1,0,0] neg_hi:[1,0,0]
	v_cmp_lt_f32_e64 s[70:71], s29, v204
	v_cmp_lt_f32_e64 s[72:73], s29, v205
	v_cmp_lt_f32_e64 s[74:75], s29, v206
	v_cmp_lt_f32_e64 s[76:77], s29, v207
	v_cndmask_b32_e64 v212, v212, v208, s[70:71]
	v_cndmask_b32_e64 v213, v213, v209, s[72:73]
	v_cndmask_b32_e64 v214, v214, v210, s[74:75]
	v_cndmask_b32_e64 v215, v215, v211, s[76:77]
	v_sqrt_f32_e32 v212, v212
	v_sqrt_f32_e32 v213, v213
	v_sqrt_f32_e32 v214, v214
	v_sqrt_f32_e32 v215, v215
	v_pk_mul_f32 v[92:93], v[200:201], v[212:213]
	v_pk_mul_f32 v[94:95], v[202:203], v[214:215]
	s_nop 1
	v_fmac_f32_dpp v92, v92, v88 row_shr:1 row_mask:0xf bank_mask:0xf
	v_fmac_f32_dpp v93, v93, v89 row_shr:1 row_mask:0xf bank_mask:0xf
	v_fmac_f32_dpp v94, v94, v90 row_shr:1 row_mask:0xf bank_mask:0xf
	v_fmac_f32_dpp v95, v95, v91 row_shr:1 row_mask:0xf bank_mask:0xf
	v_mul_f32_dpp v88, v88, v88 row_shr:1 row_mask:0xf bank_mask:0xf
	v_mul_f32_dpp v89, v89, v89 row_shr:1 row_mask:0xf bank_mask:0xf
	v_mul_f32_dpp v90, v90, v90 row_shr:1 row_mask:0xf bank_mask:0xf
	v_mul_f32_dpp v91, v91, v91 row_shr:1 row_mask:0xf bank_mask:0xf
	v_fmac_f32_dpp v92, v92, v88 row_shr:2 row_mask:0xf bank_mask:0xf
	v_fmac_f32_dpp v93, v93, v89 row_shr:2 row_mask:0xf bank_mask:0xf
	v_fmac_f32_dpp v94, v94, v90 row_shr:2 row_mask:0xf bank_mask:0xf
	v_fmac_f32_dpp v95, v95, v91 row_shr:2 row_mask:0xf bank_mask:0xf
	v_mul_f32_dpp v88, v88, v88 row_shr:2 row_mask:0xf bank_mask:0xf
	v_mul_f32_dpp v89, v89, v89 row_shr:2 row_mask:0xf bank_mask:0xf
	v_mul_f32_dpp v90, v90, v90 row_shr:2 row_mask:0xf bank_mask:0xf
	v_mul_f32_dpp v91, v91, v91 row_shr:2 row_mask:0xf bank_mask:0xf
	v_fmac_f32_dpp v92, v92, v88 row_shr:4 row_mask:0xf bank_mask:0xf
	v_fmac_f32_dpp v93, v93, v89 row_shr:4 row_mask:0xf bank_mask:0xf
	v_fmac_f32_dpp v94, v94, v90 row_shr:4 row_mask:0xf bank_mask:0xf
	v_fmac_f32_dpp v95, v95, v91 row_shr:4 row_mask:0xf bank_mask:0xf
	v_mul_f32_dpp v88, v88, v88 row_shr:4 row_mask:0xf bank_mask:0xf
	v_mul_f32_dpp v89, v89, v89 row_shr:4 row_mask:0xf bank_mask:0xf
	v_mul_f32_dpp v90, v90, v90 row_shr:4 row_mask:0xf bank_mask:0xf
	v_mul_f32_dpp v91, v91, v91 row_shr:4 row_mask:0xf bank_mask:0xf
	v_fmac_f32_dpp v92, v92, v88 row_shr:8 row_mask:0xf bank_mask:0xf
	v_fmac_f32_dpp v93, v93, v89 row_shr:8 row_mask:0xf bank_mask:0xf
	v_fmac_f32_dpp v94, v94, v90 row_shr:8 row_mask:0xf bank_mask:0xf
	v_fmac_f32_dpp v95, v95, v91 row_shr:8 row_mask:0xf bank_mask:0xf
; #define LAS __attribute__((address_space(3)))
; __device__ __forceinline__ float ex2(float x) { return __builtin_amdgcn_exp2f(x); }
; __device__ __forceinline__ float rcpf_(float x) { return __builtin_amdgcn_rcpf(x); }
; __device__ __forceinline__ void lru_phase(const Ptrs& P, LAS unsigned char* lds, int G, int wave, int lane, int tid) {
;     ...
; #pragma unroll
;             for (int i4 = 0; i4 < 4; ++i4) { if (mt == 2 && i4 >= 2) continue;
;                 const int s = 2 * mt + (i4 >> 1), half = i4 & 1, ch0 = 16 * s + 8 * half + 4 * hh;
;                 const f32x4 ls2 = *(const LAS f32x4*)(par + 7 * LB + ch0);
;                 float A4[4], B4[4];
; #pragma unroll
;                 for (int q = 0; q < 4; ++q) { const int i = 4 * i4 + q;
;                     const float rg = rcpf_(1.0f + ex2(gr[i])), ig = rcpf_(1.0f + ex2(gi[i]));
;                     const float la2 = ls2[q] * rg, a = ex2(la2), xx = (2.0f * LN2) * la2;
;                     const float poly = -xx * (1.0f + xx * (0.5f + xx * ((1.0f / 6.0f) + xx * ((1.0f / 24.0f) + xx * (1.0f / 120.0f)))));
;                     const float om = (xx > -0.25f) ? poly : (1.0f - a * a);
;                     A4[q] = a; B4[q] = __builtin_amdgcn_sqrtf(om) * (ig * xc[s][half][q]); }
;                 asm volatile("s_nop 1\n\t"
;                     LRU_DPP4("row_shr:1 row_mask:0xf bank_mask:0xf") LRU_DPP4("row_shr:2 row_mask:0xf bank_mask:0xf") LRU_DPP4("row_shr:4 row_mask:0xf bank_mask:0xf")
;                     LRU_DPP4("row_shr:8 row_mask:0xf bank_mask:0xf") LRU_DPP4("row_bcast:15 row_mask:0xa bank_mask:0xf")
;                     : "+v"(A4[0]), "+v"(A4[1]), "+v"(A4[2]), "+v"(A4[3]), "+v"(B4[0]), "+v"(B4[1]), "+v"(B4[2]), "+v"(B4[3]));
; #pragma unroll
;                 for (int q = 0; q < 4; ++q) { Av[s][half][q] = A4[q]; xc[s][half][q] = B4[q]; }
;                 __builtin_amdgcn_sched_barrier(0); }
	v_mul_f32_dpp v88, v88, v88 row_shr:8 row_mask:0xf bank_mask:0xf
	v_mul_f32_dpp v89, v89, v89 row_shr:8 row_mask:0xf bank_mask:0xf
	v_mul_f32_dpp v90, v90, v90 row_shr:8 row_mask:0xf bank_mask:0xf
	v_mul_f32_dpp v91, v91, v91 row_shr:8 row_mask:0xf bank_mask:0xf
	v_fmac_f32_dpp v92, v92, v88 row_bcast:15 row_mask:0xa bank_mask:0xf
	v_fmac_f32_dpp v93, v93, v89 row_bcast:15 row_mask:0xa bank_mask:0xf
	v_fmac_f32_dpp v94, v94, v90 row_bcast:15 row_mask:0xa bank_mask:0xf
	v_fmac_f32_dpp v95, v95, v91 row_bcast:15 row_mask:0xa bank_mask:0xf
	v_mul_f32_dpp v88, v88, v88 row_bcast:15 row_mask:0xa bank_mask:0xf
	v_mul_f32_dpp v89, v89, v89 row_bcast:15 row_mask:0xa bank_mask:0xf
	v_mul_f32_dpp v90, v90, v90 row_bcast:15 row_mask:0xa bank_mask:0xf
	v_mul_f32_dpp v91, v91, v91 row_bcast:15 row_mask:0xa bank_mask:0xf
	ds_read_b128 v[0:3], v234 offset:39296
	v_exp_f32_e32 v8, v8
	v_exp_f32_e32 v9, v9
	v_exp_f32_e32 v10, v10
	v_exp_f32_e32 v11, v11
	v_exp_f32_e32 v24, v24
	v_exp_f32_e32 v25, v25
	v_exp_f32_e32 v26, v26
	v_exp_f32_e32 v27, v27
	v_pk_add_f32 v[8:9], v[8:9], v[240:241] op_sel_hi:[1,0]
	v_pk_add_f32 v[10:11], v[10:11], v[240:241] op_sel_hi:[1,0]
	v_pk_add_f32 v[24:25], v[24:25], v[240:241] op_sel_hi:[1,0]
	v_pk_add_f32 v[26:27], v[26:27], v[240:241] op_sel_hi:[1,0]
	v_rcp_f32_e32 v8, v8
	v_rcp_f32_e32 v9, v9
	v_rcp_f32_e32 v10, v10
	v_rcp_f32_e32 v11, v11
	v_rcp_f32_e32 v24, v24
	v_rcp_f32_e32 v25, v25
	v_rcp_f32_e32 v26, v26
	v_rcp_f32_e32 v27, v27
	v_mul_f32_e32 v200, v97, v24
	v_mul_f32_e32 v201, v98, v25
	v_mul_f32_e32 v202, v102, v26
	v_mul_f32_e32 v203, v103, v27
	s_waitcnt lgkmcnt(0)
	v_pk_mul_f32 v[8:9], v[8:9], v[0:1]
	v_pk_mul_f32 v[10:11], v[10:11], v[2:3]
	v_pk_mul_f32 v[204:205], v[8:9], v[242:243] op_sel_hi:[1,0]
	v_pk_mul_f32 v[206:207], v[10:11], v[242:243] op_sel_hi:[1,0]
	v_exp_f32_e32 v96, v8
	v_exp_f32_e32 v97, v9
	v_exp_f32_e32 v98, v10
	v_exp_f32_e32 v99, v11
	v_pk_fma_f32 v[208:209], v[204:205], v[244:245], v[238:239] op_sel_hi:[1,0,0]
	v_pk_fma_f32 v[210:211], v[206:207], v[244:245], v[238:239] op_sel_hi:[1,0,0]
	v_pk_fma_f32 v[208:209], v[204:205], v[208:209], v[246:247] op_sel_hi:[1,1,0]
	v_pk_fma_f32 v[210:211], v[206:207], v[210:211], v[246:247] op_sel_hi:[1,1,0]
	v_pk_fma_f32 v[208:209], v[204:205], v[208:209], v[248:249] op_sel_hi:[1,1,0]
	v_pk_fma_f32 v[210:211], v[206:207], v[210:211], v[248:249] op_sel_hi:[1,1,0]
	v_pk_fma_f32 v[208:209], v[204:205], v[208:209], v[240:241] op_sel_hi:[1,1,0]
	v_pk_fma_f32 v[210:211], v[206:207], v[210:211], v[240:241] op_sel_hi:[1,1,0]
	v_pk_mul_f32 v[208:209], v[208:209], v[204:205] neg_lo:[0,1] neg_hi:[0,1]
	v_pk_mul_f32 v[210:211], v[210:211], v[206:207] neg_lo:[0,1] neg_hi:[0,1]
	v_pk_fma_f32 v[212:213], v[96:97], v[96:97], v[240:241] op_sel_hi:[1,1,0] neg_lo:[1,0,0] neg_hi:[1,0,0]
	v_pk_fma_f32 v[214:215], v[98:99], v[98:99], v[240:241] op_sel_hi:[1,1,0] neg_lo:[1,0,0] neg_hi:[1,0,0]
	v_cmp_lt_f32_e64 s[70:71], s29, v204
	v_cmp_lt_f32_e64 s[72:73], s29, v205
	v_cmp_lt_f32_e64 s[74:75], s29, v206
	v_cmp_lt_f32_e64 s[76:77], s29, v207
	v_cndmask_b32_e64 v212, v212, v208, s[70:71]
	v_cndmask_b32_e64 v213, v213, v209, s[72:73]
	v_cndmask_b32_e64 v214, v214, v210, s[74:75]
	v_cndmask_b32_e64 v215, v215, v211, s[76:77]
	v_sqrt_f32_e32 v212, v212
	v_sqrt_f32_e32 v213, v213
	v_sqrt_f32_e32 v214, v214
	v_sqrt_f32_e32 v215, v215
	v_pk_mul_f32 v[100:101], v[200:201], v[212:213]
	v_pk_mul_f32 v[102:103], v[202:203], v[214:215]
	s_nop 1
	v_fmac_f32_dpp v100, v100, v96 row_shr:1 row_mask:0xf bank_mask:0xf
	v_fmac_f32_dpp v101, v101, v97 row_shr:1 row_mask:0xf bank_mask:0xf
	v_fmac_f32_dpp v102, v102, v98 row_shr:1 row_mask:0xf bank_mask:0xf
	v_fmac_f32_dpp v103, v103, v99 row_shr:1 row_mask:0xf bank_mask:0xf
	v_mul_f32_dpp v96, v96, v96 row_shr:1 row_mask:0xf bank_mask:0xf
	v_mul_f32_dpp v97, v97, v97 row_shr:1 row_mask:0xf bank_mask:0xf
	v_mul_f32_dpp v98, v98, v98 row_shr:1 row_mask:0xf bank_mask:0xf
	v_mul_f32_dpp v99, v99, v99 row_shr:1 row_mask:0xf bank_mask:0xf
	v_fmac_f32_dpp v100, v100, v96 row_shr:2 row_mask:0xf bank_mask:0xf
	v_fmac_f32_dpp v101, v101, v97 row_shr:2 row_mask:0xf bank_mask:0xf
	v_fmac_f32_dpp v102, v102, v98 row_shr:2 row_mask:0xf bank_mask:0xf
	v_fmac_f32_dpp v103, v103, v99 row_shr:2 row_mask:0xf bank_mask:0xf
	v_mul_f32_dpp v96, v96, v96 row_shr:2 row_mask:0xf bank_mask:0xf
	v_mul_f32_dpp v97, v97, v97 row_shr:2 row_mask:0xf bank_mask:0xf
	v_mul_f32_dpp v98, v98, v98 row_shr:2 row_mask:0xf bank_mask:0xf
	v_mul_f32_dpp v99, v99, v99 row_shr:2 row_mask:0xf bank_mask:0xf
	v_fmac_f32_dpp v100, v100, v96 row_shr:4 row_mask:0xf bank_mask:0xf
	v_fmac_f32_dpp v101, v101, v97 row_shr:4 row_mask:0xf bank_mask:0xf
	v_fmac_f32_dpp v102, v102, v98 row_shr:4 row_mask:0xf bank_mask:0xf
	v_fmac_f32_dpp v103, v103, v99 row_shr:4 row_mask:0xf bank_mask:0xf
	v_mul_f32_dpp v96, v96, v96 row_shr:4 row_mask:0xf bank_mask:0xf
	v_mul_f32_dpp v97, v97, v97 row_shr:4 row_mask:0xf bank_mask:0xf
	v_mul_f32_dpp v98, v98, v98 row_shr:4 row_mask:0xf bank_mask:0xf
	v_mul_f32_dpp v99, v99, v99 row_shr:4 row_mask:0xf bank_mask:0xf
	v_fmac_f32_dpp v100, v100, v96 row_shr:8 row_mask:0xf bank_mask:0xf
	v_fmac_f32_dpp v101, v101, v97 row_shr:8 row_mask:0xf bank_mask:0xf
	v_fmac_f32_dpp v102, v102, v98 row_shr:8 row_mask:0xf bank_mask:0xf
	v_fmac_f32_dpp v103, v103, v99 row_shr:8 row_mask:0xf bank_mask:0xf
	v_mul_f32_dpp v96, v96, v96 row_shr:8 row_mask:0xf bank_mask:0xf
	v_mul_f32_dpp v97, v97, v97 row_shr:8 row_mask:0xf bank_mask:0xf
	v_mul_f32_dpp v98, v98, v98 row_shr:8 row_mask:0xf bank_mask:0xf
	v_mul_f32_dpp v99, v99, v99 row_shr:8 row_mask:0xf bank_mask:0xf
	v_fmac_f32_dpp v100, v100, v96 row_bcast:15 row_mask:0xa bank_mask:0xf
	v_fmac_f32_dpp v101, v101, v97 row_bcast:15 row_mask:0xa bank_mask:0xf
	v_fmac_f32_dpp v102, v102, v98 row_bcast:15 row_mask:0xa bank_mask:0xf
	v_fmac_f32_dpp v103, v103, v99 row_bcast:15 row_mask:0xa bank_mask:0xf
	v_mul_f32_dpp v96, v96, v96 row_bcast:15 row_mask:0xa bank_mask:0xf
	v_mul_f32_dpp v97, v97, v97 row_bcast:15 row_mask:0xa bank_mask:0xf
	v_mul_f32_dpp v98, v98, v98 row_bcast:15 row_mask:0xa bank_mask:0xf
	v_mul_f32_dpp v99, v99, v99 row_bcast:15 row_mask:0xa bank_mask:0xf
	ds_read_b128 v[0:3], v234 offset:39328
	v_exp_f32_e32 v12, v12
	v_exp_f32_e32 v13, v13
	v_exp_f32_e32 v14, v14
	v_exp_f32_e32 v15, v15
	v_exp_f32_e32 v28, v28
	v_exp_f32_e32 v29, v29
	v_exp_f32_e32 v30, v30
	v_exp_f32_e32 v31, v31
	v_pk_add_f32 v[12:13], v[12:13], v[240:241] op_sel_hi:[1,0]
	v_pk_add_f32 v[14:15], v[14:15], v[240:241] op_sel_hi:[1,0]
	v_pk_add_f32 v[28:29], v[28:29], v[240:241] op_sel_hi:[1,0]
	v_pk_add_f32 v[30:31], v[30:31], v[240:241] op_sel_hi:[1,0]
	v_rcp_f32_e32 v12, v12
	v_rcp_f32_e32 v13, v13
	v_rcp_f32_e32 v14, v14
	v_rcp_f32_e32 v15, v15
	v_rcp_f32_e32 v28, v28
	v_rcp_f32_e32 v29, v29
	v_rcp_f32_e32 v30, v30
	v_rcp_f32_e32 v31, v31
	v_mul_f32_e32 v200, v105, v28
	v_mul_f32_e32 v201, v106, v29
	v_mul_f32_e32 v202, v110, v30
	v_mul_f32_e32 v203, v111, v31
	s_waitcnt lgkmcnt(0)
; #define LAS __attribute__((address_space(3)))
; __device__ __forceinline__ float ex2(float x) { return __builtin_amdgcn_exp2f(x); }
; __device__ __forceinline__ float rcpf_(float x) { return __builtin_amdgcn_rcpf(x); }
; __device__ __forceinline__ void lru_phase(const Ptrs& P, LAS unsigned char* lds, int G, int wave, int lane, int tid) {
;     ...
; #pragma unroll
;             for (int i4 = 0; i4 < 4; ++i4) { if (mt == 2 && i4 >= 2) continue;
;                 const int s = 2 * mt + (i4 >> 1), half = i4 & 1, ch0 = 16 * s + 8 * half + 4 * hh;
;                 const f32x4 ls2 = *(const LAS f32x4*)(par + 7 * LB + ch0);
;                 float A4[4], B4[4];
; #pragma unroll
;                 for (int q = 0; q < 4; ++q) { const int i = 4 * i4 + q;
;                     const float rg = rcpf_(1.0f + ex2(gr[i])), ig = rcpf_(1.0f + ex2(gi[i]));
;                     const float la2 = ls2[q] * rg, a = ex2(la2), xx = (2.0f * LN2) * la2;
;                     const float poly = -xx * (1.0f + xx * (0.5f + xx * ((1.0f / 6.0f) + xx * ((1.0f / 24.0f) + xx * (1.0f / 120.0f)))));
;                     const float om = (xx > -0.25f) ? poly : (1.0f - a * a);
;                     A4[q] = a; B4[q] = __builtin_amdgcn_sqrtf(om) * (ig * xc[s][half][q]); }
;                 asm volatile("s_nop 1\n\t"
;                     LRU_DPP4("row_shr:1 row_mask:0xf bank_mask:0xf") LRU_DPP4("row_shr:2 row_mask:0xf bank_mask:0xf") LRU_DPP4("row_shr:4 row_mask:0xf bank_mask:0xf")
;                     LRU_DPP4("row_shr:8 row_mask:0xf bank_mask:0xf") LRU_DPP4("row_bcast:15 row_mask:0xa bank_mask:0xf")
;                     : "+v"(A4[0]), "+v"(A4[1]), "+v"(A4[2]), "+v"(A4[3]), "+v"(B4[0]), "+v"(B4[1]), "+v"(B4[2]), "+v"(B4[3]));
; #pragma unroll
;                 for (int q = 0; q < 4; ++q) { Av[s][half][q] = A4[q]; xc[s][half][q] = B4[q]; }
;                 __builtin_amdgcn_sched_barrier(0); }
	v_pk_mul_f32 v[12:13], v[12:13], v[0:1]
	v_pk_mul_f32 v[14:15], v[14:15], v[2:3]
	v_pk_mul_f32 v[204:205], v[12:13], v[242:243] op_sel_hi:[1,0]
	v_pk_mul_f32 v[206:207], v[14:15], v[242:243] op_sel_hi:[1,0]
	v_exp_f32_e32 v104, v12
	v_exp_f32_e32 v105, v13
	v_exp_f32_e32 v106, v14
	v_exp_f32_e32 v107, v15
	v_pk_fma_f32 v[208:209], v[204:205], v[244:245], v[238:239] op_sel_hi:[1,0,0]
	v_pk_fma_f32 v[210:211], v[206:207], v[244:245], v[238:239] op_sel_hi:[1,0,0]
	v_pk_fma_f32 v[208:209], v[204:205], v[208:209], v[246:247] op_sel_hi:[1,1,0]
	v_pk_fma_f32 v[210:211], v[206:207], v[210:211], v[246:247] op_sel_hi:[1,1,0]
	v_pk_fma_f32 v[208:209], v[204:205], v[208:209], v[248:249] op_sel_hi:[1,1,0]
	v_pk_fma_f32 v[210:211], v[206:207], v[210:211], v[248:249] op_sel_hi:[1,1,0]
	v_pk_fma_f32 v[208:209], v[204:205], v[208:209], v[240:241] op_sel_hi:[1,1,0]
	v_pk_fma_f32 v[210:211], v[206:207], v[210:211], v[240:241] op_sel_hi:[1,1,0]
	v_pk_mul_f32 v[208:209], v[208:209], v[204:205] neg_lo:[0,1] neg_hi:[0,1]
	v_pk_mul_f32 v[210:211], v[210:211], v[206:207] neg_lo:[0,1] neg_hi:[0,1]
	v_pk_fma_f32 v[212:213], v[104:105], v[104:105], v[240:241] op_sel_hi:[1,1,0] neg_lo:[1,0,0] neg_hi:[1,0,0]
	v_pk_fma_f32 v[214:215], v[106:107], v[106:107], v[240:241] op_sel_hi:[1,1,0] neg_lo:[1,0,0] neg_hi:[1,0,0]
	v_cmp_lt_f32_e64 s[70:71], s29, v204
	v_cmp_lt_f32_e64 s[72:73], s29, v205
	v_cmp_lt_f32_e64 s[74:75], s29, v206
	v_cmp_lt_f32_e64 s[76:77], s29, v207
	v_cndmask_b32_e64 v212, v212, v208, s[70:71]
	v_cndmask_b32_e64 v213, v213, v209, s[72:73]
	v_cndmask_b32_e64 v214, v214, v210, s[74:75]
	v_cndmask_b32_e64 v215, v215, v211, s[76:77]
	v_sqrt_f32_e32 v212, v212
	v_sqrt_f32_e32 v213, v213
	v_sqrt_f32_e32 v214, v214
	v_sqrt_f32_e32 v215, v215
	v_pk_mul_f32 v[108:109], v[200:201], v[212:213]
	v_pk_mul_f32 v[110:111], v[202:203], v[214:215]
	s_nop 1
	v_fmac_f32_dpp v108, v108, v104 row_shr:1 row_mask:0xf bank_mask:0xf
	v_fmac_f32_dpp v109, v109, v105 row_shr:1 row_mask:0xf bank_mask:0xf
	v_fmac_f32_dpp v110, v110, v106 row_shr:1 row_mask:0xf bank_mask:0xf
	v_fmac_f32_dpp v111, v111, v107 row_shr:1 row_mask:0xf bank_mask:0xf
	v_mul_f32_dpp v104, v104, v104 row_shr:1 row_mask:0xf bank_mask:0xf
	v_mul_f32_dpp v105, v105, v105 row_shr:1 row_mask:0xf bank_mask:0xf
	v_mul_f32_dpp v106, v106, v106 row_shr:1 row_mask:0xf bank_mask:0xf
	v_mul_f32_dpp v107, v107, v107 row_shr:1 row_mask:0xf bank_mask:0xf
	v_fmac_f32_dpp v108, v108, v104 row_shr:2 row_mask:0xf bank_mask:0xf
	v_fmac_f32_dpp v109, v109, v105 row_shr:2 row_mask:0xf bank_mask:0xf
	v_fmac_f32_dpp v110, v110, v106 row_shr:2 row_mask:0xf bank_mask:0xf
	v_fmac_f32_dpp v111, v111, v107 row_shr:2 row_mask:0xf bank_mask:0xf
	v_mul_f32_dpp v104, v104, v104 row_shr:2 row_mask:0xf bank_mask:0xf
	v_mul_f32_dpp v105, v105, v105 row_shr:2 row_mask:0xf bank_mask:0xf
	v_mul_f32_dpp v106, v106, v106 row_shr:2 row_mask:0xf bank_mask:0xf
	v_mul_f32_dpp v107, v107, v107 row_shr:2 row_mask:0xf bank_mask:0xf
	v_fmac_f32_dpp v108, v108, v104 row_shr:4 row_mask:0xf bank_mask:0xf
	v_fmac_f32_dpp v109, v109, v105 row_shr:4 row_mask:0xf bank_mask:0xf
	v_fmac_f32_dpp v110, v110, v106 row_shr:4 row_mask:0xf bank_mask:0xf
	v_fmac_f32_dpp v111, v111, v107 row_shr:4 row_mask:0xf bank_mask:0xf
	v_mul_f32_dpp v104, v104, v104 row_shr:4 row_mask:0xf bank_mask:0xf
	v_mul_f32_dpp v105, v105, v105 row_shr:4 row_mask:0xf bank_mask:0xf
	v_mul_f32_dpp v106, v106, v106 row_shr:4 row_mask:0xf bank_mask:0xf
	v_mul_f32_dpp v107, v107, v107 row_shr:4 row_mask:0xf bank_mask:0xf
	v_fmac_f32_dpp v108, v108, v104 row_shr:8 row_mask:0xf bank_mask:0xf
	v_fmac_f32_dpp v109, v109, v105 row_shr:8 row_mask:0xf bank_mask:0xf
	v_fmac_f32_dpp v110, v110, v106 row_shr:8 row_mask:0xf bank_mask:0xf
	v_fmac_f32_dpp v111, v111, v107 row_shr:8 row_mask:0xf bank_mask:0xf
	v_mul_f32_dpp v104, v104, v104 row_shr:8 row_mask:0xf bank_mask:0xf
	v_mul_f32_dpp v105, v105, v105 row_shr:8 row_mask:0xf bank_mask:0xf
	v_mul_f32_dpp v106, v106, v106 row_shr:8 row_mask:0xf bank_mask:0xf
	v_mul_f32_dpp v107, v107, v107 row_shr:8 row_mask:0xf bank_mask:0xf
	v_fmac_f32_dpp v108, v108, v104 row_bcast:15 row_mask:0xa bank_mask:0xf
	v_fmac_f32_dpp v109, v109, v105 row_bcast:15 row_mask:0xa bank_mask:0xf
	v_fmac_f32_dpp v110, v110, v106 row_bcast:15 row_mask:0xa bank_mask:0xf
	v_fmac_f32_dpp v111, v111, v107 row_bcast:15 row_mask:0xa bank_mask:0xf
	v_mul_f32_dpp v104, v104, v104 row_bcast:15 row_mask:0xa bank_mask:0xf
	v_mul_f32_dpp v105, v105, v105 row_bcast:15 row_mask:0xa bank_mask:0xf
	v_mul_f32_dpp v106, v106, v106 row_bcast:15 row_mask:0xa bank_mask:0xf
	v_mul_f32_dpp v107, v107, v107 row_bcast:15 row_mask:0xa bank_mask:0xf

; #define LAS __attribute__((address_space(3)))
; __device__ __forceinline__ void lru_phase(const Ptrs& P, LAS unsigned char* lds, int G, int wave, int lane, int tid) {
;     ...
;         for (int mt = 0; mt < 3; ++mt) {
;             f32x16 gr, gi;
; #pragma unroll
;             for (int i = 0; i < 16; ++i) { gr[i] = 0.f; gi[i] = 0.f; }
;             const LAS bf16x8* wa = (const LAS bf16x8*)(lds + L_WGF) + (size_t)(mt * 6) * 64 + lane;
;             const LAS bf16x8* wb = (const LAS bf16x8*)(lds + L_WGF) + (size_t)((3 + mt) * 6) * 64 + lane;
; #pragma unroll
;             for (int s = 0; s < 5; ++s) { gr = MFMA32(wa[s * 64], xf[s], gr); gi = MFMA32(wb[s * 64], xf[s], gi); }
;             gr = MFMA32(wa[5 * 64], xone, gr); gi = MFMA32(wb[5 * 64], xone, gi);
;             __builtin_amdgcn_sched_barrier(0);
; #pragma unroll
;             for (int i4 = 0; i4 < 4; ++i4) { if (mt == 2 && i4 >= 2) continue;
;                 const int s = 2 * mt + (i4 >> 1), half = i4 & 1, ch0 = 16 * s + 8 * half + 4 * hh;
;                 const f32x4 ls2 = *(const LAS f32x4*)(par + 7 * LB + ch0);
;                 float A4[4], B4[4];
; #pragma unroll
;                 for (int q = 0; q < 4; ++q) { const int i = 4 * i4 + q;
;                     const float rg = rcpf_(1.0f + ex2(gr[i])), ig = rcpf_(1.0f + ex2(gi[i]));
;                     const float la2 = ls2[q] * rg, a = ex2(la2), xx = (2.0f * LN2) * la2;
;                     const float poly = -xx * (1.0f + xx * (0.5f + xx * ((1.0f / 6.0f) + xx * ((1.0f / 24.0f) + xx * (1.0f / 120.0f)))));
;                     const float om = (xx > -0.25f) ? poly : (1.0f - a * a);
;                     A4[q] = a; B4[q] = __builtin_amdgcn_sqrtf(om) * (ig * xc[s][half][q]); }
;                 asm volatile("s_nop 1\n\t"
;                     LRU_DPP4("row_shr:1 row_mask:0xf bank_mask:0xf") LRU_DPP4("row_shr:2 row_mask:0xf bank_mask:0xf") LRU_DPP4("row_shr:4 row_mask:0xf bank_mask:0xf")
;                     LRU_DPP4("row_shr:8 row_mask:0xf bank_mask:0xf") LRU_DPP4("row_bcast:15 row_mask:0xa bank_mask:0xf")
;                     : "+v"(A4[0]), "+v"(A4[1]), "+v"(A4[2]), "+v"(A4[3]), "+v"(B4[0]), "+v"(B4[1]), "+v"(B4[2]), "+v"(B4[3]));
; #pragma unroll
;                 for (int q = 0; q < 4; ++q) { Av[s][half][q] = A4[q]; xc[s][half][q] = B4[q]; }
;                 __builtin_amdgcn_sched_barrier(0); }
	ds_read_b128 v[0:3], v237 offset:12288
	ds_read_b128 v[140:143], v237 offset:13312
	ds_read_b128 v[16:19], v237 offset:30720
	ds_read_b128 v[144:147], v237 offset:31744
	s_waitcnt lgkmcnt(3)
	v_mfma_f32_32x32x16_bf16 v[0:15], v[0:3], v[36:39], 0
	s_waitcnt lgkmcnt(1)
	v_mfma_f32_32x32x16_bf16 v[16:31], v[16:19], v[36:39], 0
	v_mfma_f32_32x32x16_bf16 v[0:15], v[140:143], v[40:43], v[0:15]
	s_waitcnt lgkmcnt(0)
	v_mfma_f32_32x32x16_bf16 v[16:31], v[144:147], v[40:43], v[16:31]
	ds_read_b128 v[36:39], v237 offset:14336
	ds_read_b128 v[40:43], v237 offset:15360
	s_waitcnt lgkmcnt(1)
	v_mfma_f32_32x32x16_bf16 v[0:15], v[36:39], v[76:79], v[0:15]
	ds_read_b128 v[36:39], v237 offset:32768
	ds_read_b128 v[140:143], v237 offset:33792
	s_waitcnt lgkmcnt(1)
	v_mfma_f32_32x32x16_bf16 v[16:31], v[36:39], v[76:79], v[16:31]
	v_mfma_f32_32x32x16_bf16 v[0:15], v[40:43], v[112:115], v[0:15]
	ds_read_b128 v[36:39], v237 offset:16384
	ds_read_b128 v[40:43], v237 offset:17408
	s_waitcnt lgkmcnt(2)
	v_mfma_f32_32x32x16_bf16 v[16:31], v[140:143], v[112:115], v[16:31]
	s_waitcnt lgkmcnt(1)
	v_mfma_f32_32x32x16_bf16 v[0:15], v[36:39], v[124:127], v[0:15]
	ds_read_b128 v[36:39], v237 offset:34816
	ds_read_b128 v[76:79], v237 offset:35840
	s_waitcnt lgkmcnt(1)
	v_mfma_f32_32x32x16_bf16 v[16:31], v[36:39], v[124:127], v[16:31]
	v_mfma_f32_32x32x16_bf16 v[0:15], v[40:43], v[32:35], v[0:15]
	s_waitcnt lgkmcnt(0)
	v_mfma_f32_32x32x16_bf16 v[16:31], v[76:79], v[32:35], v[16:31]
	s_nop 9
	ds_read_b128 v[8:11], v234 offset:39360
	v_exp_f32_e32 v0, v0
	v_exp_f32_e32 v1, v1
	v_exp_f32_e32 v2, v2
	v_exp_f32_e32 v3, v3
	v_exp_f32_e32 v16, v16
	v_exp_f32_e32 v17, v17
	v_exp_f32_e32 v18, v18
	v_exp_f32_e32 v19, v19
	v_pk_add_f32 v[0:1], v[0:1], v[240:241] op_sel_hi:[1,0]
	v_pk_add_f32 v[2:3], v[2:3], v[240:241] op_sel_hi:[1,0]
	v_pk_add_f32 v[16:17], v[16:17], v[240:241] op_sel_hi:[1,0]
	v_pk_add_f32 v[18:19], v[18:19], v[240:241] op_sel_hi:[1,0]
	v_rcp_f32_e32 v0, v0
	v_rcp_f32_e32 v1, v1
	v_rcp_f32_e32 v2, v2
	v_rcp_f32_e32 v3, v3
	v_rcp_f32_e32 v16, v16
	v_rcp_f32_e32 v17, v17
	v_rcp_f32_e32 v18, v18
	v_rcp_f32_e32 v19, v19
	v_mul_f32_e32 v200, v136, v16
	v_mul_f32_e32 v201, v129, v17
	v_mul_f32_e32 v202, v116, v18
	v_mul_f32_e32 v203, v119, v19
	s_waitcnt lgkmcnt(0)
	v_pk_mul_f32 v[0:1], v[0:1], v[8:9]
	v_pk_mul_f32 v[2:3], v[2:3], v[10:11]
	v_pk_mul_f32 v[204:205], v[0:1], v[242:243] op_sel_hi:[1,0]
	v_pk_mul_f32 v[206:207], v[2:3], v[242:243] op_sel_hi:[1,0]
	v_exp_f32_e32 v0, v0
	v_exp_f32_e32 v1, v1
	v_exp_f32_e32 v2, v2
	v_exp_f32_e32 v3, v3
	v_pk_fma_f32 v[208:209], v[204:205], v[244:245], v[238:239] op_sel_hi:[1,0,0]
	v_pk_fma_f32 v[210:211], v[206:207], v[244:245], v[238:239] op_sel_hi:[1,0,0]
	v_pk_fma_f32 v[208:209], v[204:205], v[208:209], v[246:247] op_sel_hi:[1,1,0]
	v_pk_fma_f32 v[210:211], v[206:207], v[210:211], v[246:247] op_sel_hi:[1,1,0]
	v_pk_fma_f32 v[208:209], v[204:205], v[208:209], v[248:249] op_sel_hi:[1,1,0]
	v_pk_fma_f32 v[210:211], v[206:207], v[210:211], v[248:249] op_sel_hi:[1,1,0]
	v_pk_fma_f32 v[208:209], v[204:205], v[208:209], v[240:241] op_sel_hi:[1,1,0]
	v_pk_fma_f32 v[210:211], v[206:207], v[210:211], v[240:241] op_sel_hi:[1,1,0]
	v_pk_mul_f32 v[208:209], v[208:209], v[204:205] neg_lo:[0,1] neg_hi:[0,1]
	v_pk_mul_f32 v[210:211], v[210:211], v[206:207] neg_lo:[0,1] neg_hi:[0,1]
	v_pk_fma_f32 v[212:213], v[0:1], v[0:1], v[240:241] op_sel_hi:[1,1,0] neg_lo:[1,0,0] neg_hi:[1,0,0]
	v_pk_fma_f32 v[214:215], v[2:3], v[2:3], v[240:241] op_sel_hi:[1,1,0] neg_lo:[1,0,0] neg_hi:[1,0,0]
	v_cmp_lt_f32_e64 s[70:71], s29, v204
	v_cmp_lt_f32_e64 s[72:73], s29, v205
	v_cmp_lt_f32_e64 s[74:75], s29, v206
	v_cmp_lt_f32_e64 s[76:77], s29, v207
	v_cndmask_b32_e64 v212, v212, v208, s[70:71]
	v_cndmask_b32_e64 v213, v213, v209, s[72:73]
	v_cndmask_b32_e64 v214, v214, v210, s[74:75]
	v_cndmask_b32_e64 v215, v215, v211, s[76:77]
	v_sqrt_f32_e32 v212, v212
	v_sqrt_f32_e32 v213, v213
	v_sqrt_f32_e32 v214, v214
	v_sqrt_f32_e32 v215, v215
	v_pk_mul_f32 v[8:9], v[200:201], v[212:213]
	v_pk_mul_f32 v[10:11], v[202:203], v[214:215]
	s_nop 1
	v_fmac_f32_dpp v8, v8, v0 row_shr:1 row_mask:0xf bank_mask:0xf
	v_fmac_f32_dpp v9, v9, v1 row_shr:1 row_mask:0xf bank_mask:0xf
	v_fmac_f32_dpp v10, v10, v2 row_shr:1 row_mask:0xf bank_mask:0xf
	v_fmac_f32_dpp v11, v11, v3 row_shr:1 row_mask:0xf bank_mask:0xf
	v_mul_f32_dpp v0, v0, v0 row_shr:1 row_mask:0xf bank_mask:0xf
	v_mul_f32_dpp v1, v1, v1 row_shr:1 row_mask:0xf bank_mask:0xf
	v_mul_f32_dpp v2, v2, v2 row_shr:1 row_mask:0xf bank_mask:0xf
	v_mul_f32_dpp v3, v3, v3 row_shr:1 row_mask:0xf bank_mask:0xf
	v_fmac_f32_dpp v8, v8, v0 row_shr:2 row_mask:0xf bank_mask:0xf
	v_fmac_f32_dpp v9, v9, v1 row_shr:2 row_mask:0xf bank_mask:0xf
	v_fmac_f32_dpp v10, v10, v2 row_shr:2 row_mask:0xf bank_mask:0xf
	v_fmac_f32_dpp v11, v11, v3 row_shr:2 row_mask:0xf bank_mask:0xf
	v_mul_f32_dpp v0, v0, v0 row_shr:2 row_mask:0xf bank_mask:0xf
	v_mul_f32_dpp v1, v1, v1 row_shr:2 row_mask:0xf bank_mask:0xf
	v_mul_f32_dpp v2, v2, v2 row_shr:2 row_mask:0xf bank_mask:0xf
	v_mul_f32_dpp v3, v3, v3 row_shr:2 row_mask:0xf bank_mask:0xf
	v_fmac_f32_dpp v8, v8, v0 row_shr:4 row_mask:0xf bank_mask:0xf
	v_fmac_f32_dpp v9, v9, v1 row_shr:4 row_mask:0xf bank_mask:0xf
	v_fmac_f32_dpp v10, v10, v2 row_shr:4 row_mask:0xf bank_mask:0xf
	v_fmac_f32_dpp v11, v11, v3 row_shr:4 row_mask:0xf bank_mask:0xf
	v_mul_f32_dpp v0, v0, v0 row_shr:4 row_mask:0xf bank_mask:0xf
	v_mul_f32_dpp v1, v1, v1 row_shr:4 row_mask:0xf bank_mask:0xf
	v_mul_f32_dpp v2, v2, v2 row_shr:4 row_mask:0xf bank_mask:0xf
	v_mul_f32_dpp v3, v3, v3 row_shr:4 row_mask:0xf bank_mask:0xf
; #define LAS __attribute__((address_space(3)))
; __device__ __forceinline__ float ex2(float x) { return __builtin_amdgcn_exp2f(x); }
; __device__ __forceinline__ float rcpf_(float x) { return __builtin_amdgcn_rcpf(x); }
; __device__ __forceinline__ void lru_phase(const Ptrs& P, LAS unsigned char* lds, int G, int wave, int lane, int tid) {
;     ...
; #pragma unroll
;             for (int i4 = 0; i4 < 4; ++i4) { if (mt == 2 && i4 >= 2) continue;
;                 const int s = 2 * mt + (i4 >> 1), half = i4 & 1, ch0 = 16 * s + 8 * half + 4 * hh;
;                 const f32x4 ls2 = *(const LAS f32x4*)(par + 7 * LB + ch0);
;                 float A4[4], B4[4];
; #pragma unroll
;                 for (int q = 0; q < 4; ++q) { const int i = 4 * i4 + q;
;                     const float rg = rcpf_(1.0f + ex2(gr[i])), ig = rcpf_(1.0f + ex2(gi[i]));
;                     const float la2 = ls2[q] * rg, a = ex2(la2), xx = (2.0f * LN2) * la2;
;                     const float poly = -xx * (1.0f + xx * (0.5f + xx * ((1.0f / 6.0f) + xx * ((1.0f / 24.0f) + xx * (1.0f / 120.0f)))));
;                     const float om = (xx > -0.25f) ? poly : (1.0f - a * a);
;                     A4[q] = a; B4[q] = __builtin_amdgcn_sqrtf(om) * (ig * xc[s][half][q]); }
;                 asm volatile("s_nop 1\n\t"
;                     LRU_DPP4("row_shr:1 row_mask:0xf bank_mask:0xf") LRU_DPP4("row_shr:2 row_mask:0xf bank_mask:0xf") LRU_DPP4("row_shr:4 row_mask:0xf bank_mask:0xf")
;                     LRU_DPP4("row_shr:8 row_mask:0xf bank_mask:0xf") LRU_DPP4("row_bcast:15 row_mask:0xa bank_mask:0xf")
;                     : "+v"(A4[0]), "+v"(A4[1]), "+v"(A4[2]), "+v"(A4[3]), "+v"(B4[0]), "+v"(B4[1]), "+v"(B4[2]), "+v"(B4[3]));
; #pragma unroll
;                 for (int q = 0; q < 4; ++q) { Av[s][half][q] = A4[q]; xc[s][half][q] = B4[q]; }
;                 __builtin_amdgcn_sched_barrier(0); }
	v_fmac_f32_dpp v8, v8, v0 row_shr:8 row_mask:0xf bank_mask:0xf
	v_fmac_f32_dpp v9, v9, v1 row_shr:8 row_mask:0xf bank_mask:0xf
	v_fmac_f32_dpp v10, v10, v2 row_shr:8 row_mask:0xf bank_mask:0xf
	v_fmac_f32_dpp v11, v11, v3 row_shr:8 row_mask:0xf bank_mask:0xf
	v_mul_f32_dpp v0, v0, v0 row_shr:8 row_mask:0xf bank_mask:0xf
	v_mul_f32_dpp v1, v1, v1 row_shr:8 row_mask:0xf bank_mask:0xf
	v_mul_f32_dpp v2, v2, v2 row_shr:8 row_mask:0xf bank_mask:0xf
	v_mul_f32_dpp v3, v3, v3 row_shr:8 row_mask:0xf bank_mask:0xf
	v_fmac_f32_dpp v8, v8, v0 row_bcast:15 row_mask:0xa bank_mask:0xf
	v_fmac_f32_dpp v9, v9, v1 row_bcast:15 row_mask:0xa bank_mask:0xf
	v_fmac_f32_dpp v10, v10, v2 row_bcast:15 row_mask:0xa bank_mask:0xf
	v_fmac_f32_dpp v11, v11, v3 row_bcast:15 row_mask:0xa bank_mask:0xf
	v_mul_f32_dpp v0, v0, v0 row_bcast:15 row_mask:0xa bank_mask:0xf
	v_mul_f32_dpp v1, v1, v1 row_bcast:15 row_mask:0xa bank_mask:0xf
	v_mul_f32_dpp v2, v2, v2 row_bcast:15 row_mask:0xa bank_mask:0xf
	v_mul_f32_dpp v3, v3, v3 row_bcast:15 row_mask:0xa bank_mask:0xf
	ds_read_b128 v[12:15], v234 offset:39392
	v_exp_f32_e32 v4, v4
	v_exp_f32_e32 v5, v5
	v_exp_f32_e32 v6, v6
	v_exp_f32_e32 v7, v7
	v_exp_f32_e32 v20, v20
	v_exp_f32_e32 v21, v21
	v_exp_f32_e32 v22, v22
	v_exp_f32_e32 v23, v23
	v_pk_add_f32 v[4:5], v[4:5], v[240:241] op_sel_hi:[1,0]
	v_pk_add_f32 v[6:7], v[6:7], v[240:241] op_sel_hi:[1,0]
	v_pk_add_f32 v[20:21], v[20:21], v[240:241] op_sel_hi:[1,0]
	v_pk_add_f32 v[22:23], v[22:23], v[240:241] op_sel_hi:[1,0]
	v_rcp_f32_e32 v4, v4
	v_rcp_f32_e32 v5, v5
	v_rcp_f32_e32 v6, v6
	v_rcp_f32_e32 v7, v7
	v_rcp_f32_e32 v20, v20
	v_rcp_f32_e32 v21, v21
	v_rcp_f32_e32 v22, v22
	v_rcp_f32_e32 v23, v23
	v_mul_f32_e32 v200, v120, v20
	v_mul_f32_e32 v201, v118, v21
	v_mul_f32_e32 v202, v117, v22
	v_mul_f32_e32 v203, v123, v23
	s_waitcnt lgkmcnt(0)
	v_pk_mul_f32 v[4:5], v[4:5], v[12:13]
	v_pk_mul_f32 v[6:7], v[6:7], v[14:15]
	v_pk_mul_f32 v[204:205], v[4:5], v[242:243] op_sel_hi:[1,0]
	v_pk_mul_f32 v[206:207], v[6:7], v[242:243] op_sel_hi:[1,0]
	v_exp_f32_e32 v4, v4
	v_exp_f32_e32 v5, v5
	v_exp_f32_e32 v6, v6
	v_exp_f32_e32 v7, v7
	v_pk_fma_f32 v[208:209], v[204:205], v[244:245], v[238:239] op_sel_hi:[1,0,0]
	v_pk_fma_f32 v[210:211], v[206:207], v[244:245], v[238:239] op_sel_hi:[1,0,0]
	v_pk_fma_f32 v[208:209], v[204:205], v[208:209], v[246:247] op_sel_hi:[1,1,0]
	v_pk_fma_f32 v[210:211], v[206:207], v[210:211], v[246:247] op_sel_hi:[1,1,0]
	v_pk_fma_f32 v[208:209], v[204:205], v[208:209], v[248:249] op_sel_hi:[1,1,0]
	v_pk_fma_f32 v[210:211], v[206:207], v[210:211], v[248:249] op_sel_hi:[1,1,0]
	v_pk_fma_f32 v[208:209], v[204:205], v[208:209], v[240:241] op_sel_hi:[1,1,0]
	v_pk_fma_f32 v[210:211], v[206:207], v[210:211], v[240:241] op_sel_hi:[1,1,0]
	v_pk_mul_f32 v[208:209], v[208:209], v[204:205] neg_lo:[0,1] neg_hi:[0,1]
	v_pk_mul_f32 v[210:211], v[210:211], v[206:207] neg_lo:[0,1] neg_hi:[0,1]
	v_pk_fma_f32 v[212:213], v[4:5], v[4:5], v[240:241] op_sel_hi:[1,1,0] neg_lo:[1,0,0] neg_hi:[1,0,0]
	v_pk_fma_f32 v[214:215], v[6:7], v[6:7], v[240:241] op_sel_hi:[1,1,0] neg_lo:[1,0,0] neg_hi:[1,0,0]
	v_cmp_lt_f32_e64 s[70:71], s29, v204
	v_cmp_lt_f32_e64 s[72:73], s29, v205
	v_cmp_lt_f32_e64 s[74:75], s29, v206
	v_cmp_lt_f32_e64 s[76:77], s29, v207
	v_cndmask_b32_e64 v212, v212, v208, s[70:71]
	v_cndmask_b32_e64 v213, v213, v209, s[72:73]
	v_cndmask_b32_e64 v214, v214, v210, s[74:75]
	v_cndmask_b32_e64 v215, v215, v211, s[76:77]
	v_sqrt_f32_e32 v212, v212
	v_sqrt_f32_e32 v213, v213
	v_sqrt_f32_e32 v214, v214
	v_sqrt_f32_e32 v215, v215
	v_pk_mul_f32 v[12:13], v[200:201], v[212:213]
	v_pk_mul_f32 v[14:15], v[202:203], v[214:215]
	s_nop 1
	v_fmac_f32_dpp v12, v12, v4 row_shr:1 row_mask:0xf bank_mask:0xf
	v_fmac_f32_dpp v13, v13, v5 row_shr:1 row_mask:0xf bank_mask:0xf
	v_fmac_f32_dpp v14, v14, v6 row_shr:1 row_mask:0xf bank_mask:0xf
	v_fmac_f32_dpp v15, v15, v7 row_shr:1 row_mask:0xf bank_mask:0xf
	v_mul_f32_dpp v4, v4, v4 row_shr:1 row_mask:0xf bank_mask:0xf
	v_mul_f32_dpp v5, v5, v5 row_shr:1 row_mask:0xf bank_mask:0xf
	v_mul_f32_dpp v6, v6, v6 row_shr:1 row_mask:0xf bank_mask:0xf
	v_mul_f32_dpp v7, v7, v7 row_shr:1 row_mask:0xf bank_mask:0xf
	v_fmac_f32_dpp v12, v12, v4 row_shr:2 row_mask:0xf bank_mask:0xf
	v_fmac_f32_dpp v13, v13, v5 row_shr:2 row_mask:0xf bank_mask:0xf
	v_fmac_f32_dpp v14, v14, v6 row_shr:2 row_mask:0xf bank_mask:0xf
	v_fmac_f32_dpp v15, v15, v7 row_shr:2 row_mask:0xf bank_mask:0xf
	v_mul_f32_dpp v4, v4, v4 row_shr:2 row_mask:0xf bank_mask:0xf
	v_mul_f32_dpp v5, v5, v5 row_shr:2 row_mask:0xf bank_mask:0xf
	v_mul_f32_dpp v6, v6, v6 row_shr:2 row_mask:0xf bank_mask:0xf
	v_mul_f32_dpp v7, v7, v7 row_shr:2 row_mask:0xf bank_mask:0xf
	v_fmac_f32_dpp v12, v12, v4 row_shr:4 row_mask:0xf bank_mask:0xf
	v_fmac_f32_dpp v13, v13, v5 row_shr:4 row_mask:0xf bank_mask:0xf
	v_fmac_f32_dpp v14, v14, v6 row_shr:4 row_mask:0xf bank_mask:0xf
	v_fmac_f32_dpp v15, v15, v7 row_shr:4 row_mask:0xf bank_mask:0xf
	v_mul_f32_dpp v4, v4, v4 row_shr:4 row_mask:0xf bank_mask:0xf
	v_mul_f32_dpp v5, v5, v5 row_shr:4 row_mask:0xf bank_mask:0xf
	v_mul_f32_dpp v6, v6, v6 row_shr:4 row_mask:0xf bank_mask:0xf
	v_mul_f32_dpp v7, v7, v7 row_shr:4 row_mask:0xf bank_mask:0xf
	v_fmac_f32_dpp v12, v12, v4 row_shr:8 row_mask:0xf bank_mask:0xf
	v_fmac_f32_dpp v13, v13, v5 row_shr:8 row_mask:0xf bank_mask:0xf
	v_fmac_f32_dpp v14, v14, v6 row_shr:8 row_mask:0xf bank_mask:0xf
	v_fmac_f32_dpp v15, v15, v7 row_shr:8 row_mask:0xf bank_mask:0xf
	v_mul_f32_dpp v4, v4, v4 row_shr:8 row_mask:0xf bank_mask:0xf
	v_mul_f32_dpp v5, v5, v5 row_shr:8 row_mask:0xf bank_mask:0xf
	v_mul_f32_dpp v6, v6, v6 row_shr:8 row_mask:0xf bank_mask:0xf
	v_mul_f32_dpp v7, v7, v7 row_shr:8 row_mask:0xf bank_mask:0xf
	v_fmac_f32_dpp v12, v12, v4 row_bcast:15 row_mask:0xa bank_mask:0xf
	v_fmac_f32_dpp v13, v13, v5 row_bcast:15 row_mask:0xa bank_mask:0xf
	v_fmac_f32_dpp v14, v14, v6 row_bcast:15 row_mask:0xa bank_mask:0xf
	v_fmac_f32_dpp v15, v15, v7 row_bcast:15 row_mask:0xa bank_mask:0xf
	v_mul_f32_dpp v4, v4, v4 row_bcast:15 row_mask:0xa bank_mask:0xf
	v_mul_f32_dpp v5, v5, v5 row_bcast:15 row_mask:0xa bank_mask:0xf
	v_mul_f32_dpp v6, v6, v6 row_bcast:15 row_mask:0xa bank_mask:0xf
	v_mul_f32_dpp v7, v7, v7 row_bcast:15 row_mask:0xa bank_mask:0xf

; #define LAS __attribute__((address_space(3)))
; __device__ __forceinline__ void lru_phase(const Ptrs& P, LAS unsigned char* lds, int G, int wave, int lane, int tid) {
;     ...
;         v2u graw_[10];
;         { const bf16* gp = U0 + (size_t)M * LW + ((size_t)(((b * 128 + (tloc >> 5)) * 16 + hd) * 10) * 64 + lane) * 4;
; #pragma unroll
;           for (int gq = 0; gq < 10; ++gq) graw_[gq] = *(const v2u*)(gp + gq * 256); }
;         if (r == 31) { LAS float* cp = (LAS float*)(lds + L_COMP) + wave * 160 + 4 * hh;
; #pragma unroll
;             for (int s = 0; s < 5; ++s)
; #pragma unroll
;                 for (int half = 0; half < 2; ++half) { const int ch0 = 16 * s + 8 * half;
;                     *(LAS f32x4*)(cp + ch0) = (f32x4){Av[s][half][0], Av[s][half][1], Av[s][half][2], Av[s][half][3]};
;                     *(LAS f32x4*)(cp + 80 + ch0) = (f32x4){xc[s][half][0], xc[s][half][1], xc[s][half][2], xc[s][half][3]}; } }
	s_lshl_b32 s6, s31, 11
	s_lshr_b32 s7, s34, 1
	s_and_b32 s37, s20, 15
	s_add_i32 s7, s7, s6
	s_or_b32 s6, s7, s37
	s_mul_i32 s6, s6, 10
	s_ashr_i32 s7, s6, 31
	s_lshl_b64 s[6:7], s[6:7], 9
	v_lshl_add_u64 v[16:17], v[130:131], 0, s[6:7]
	global_load_dwordx2 v[200:201], v[16:17], off
	global_load_dwordx2 v[196:197], v[16:17], off offset:512
	global_load_dwordx2 v[194:195], v[16:17], off offset:1024
	global_load_dwordx2 v[192:193], v[16:17], off offset:1536
	global_load_dwordx2 v[190:191], v[16:17], off offset:2048
	global_load_dwordx2 v[188:189], v[16:17], off offset:2560
	global_load_dwordx2 v[182:183], v[16:17], off offset:3072
	global_load_dwordx2 v[180:181], v[16:17], off offset:3584
	v_add_co_u32_e32 v16, vcc, 0x1000, v16
	s_nop 1
	v_addc_co_u32_e32 v17, vcc, 0, v17, vcc
	global_load_dwordx2 v[178:179], v[16:17], off
	global_load_dwordx2 v[176:177], v[16:17], off offset:512
	s_and_saveexec_b64 s[6:7], s[2:3]
	s_cbranch_execz .LBB0_310
	v_add_u32_e32 v16, s27, v233
	ds_write_b128 v16, v[44:47] offset:39424
	ds_write_b128 v16, v[48:51] offset:39744
	ds_write_b128 v16, v[52:55] offset:39456
	ds_write_b128 v16, v[56:59] offset:39776
	ds_write_b128 v16, v[60:63] offset:39488
	ds_write_b128 v16, v[64:67] offset:39808
	ds_write_b128 v16, v[68:71] offset:39520
	ds_write_b128 v16, v[72:75] offset:39840
	ds_write_b128 v16, v[80:83] offset:39552
	ds_write_b128 v16, v[84:87] offset:39872
	ds_write_b128 v16, v[88:91] offset:39584
	ds_write_b128 v16, v[92:95] offset:39904
	ds_write_b128 v16, v[96:99] offset:39616
	ds_write_b128 v16, v[100:103] offset:39936
	ds_write_b128 v16, v[104:107] offset:39648
	ds_write_b128 v16, v[108:111] offset:39968
	ds_write_b128 v16, v[0:3] offset:39680
	ds_write_b128 v16, v[8:11] offset:40000
	ds_write_b128 v16, v[4:7] offset:39712
	ds_write_b128 v16, v[12:15] offset:40032
